# sample-compress on 96 WGs overlapped with prompt attention + conv-epilogue row shuffles as DPP rotates
# speedup vs baseline: 1.0250x; 1.0250x over previous
.LBB0_686:
	s_mov_b32 s2, -1
	s_waitcnt lgkmcnt(0)
	s_barrier
	s_ashr_i32 s6, s87, 2
	v_mbcnt_lo_u32_b32 v0, s2, 0
	v_mbcnt_hi_u32_b32 v164, s2, v0
	s_and_b32 s2, s87, 3
	s_lshl_b32 s8, s6, 8
	s_ashr_i32 s7, s6, 31
	v_ashrrev_i32_e32 v8, 31, v164
	s_ashr_i32 s9, s8, 31
	s_lshl_b32 s10, s2, 6
	s_lshl_b32 s18, s6, 14
	s_lshl_b64 s[14:15], s[6:7], 13
	s_lshl_b32 s3, s2, 9
	v_lshrrev_b32_e32 v0, 28, v8
	s_cmp_lt_u32 s87, 4
	s_mov_b32 s4, 0x29f4c000
	v_add_u32_e32 v0, v164, v0
	v_lshlrev_b32_e32 v9, 4, v164
	s_cselect_b32 s19, s4, 0x2a74c000
	s_mov_b32 s4, 0x29e4c000
	v_ashrrev_i32_e32 v168, 4, v0
	v_and_b32_e32 v0, -16, v0
	v_lshl_add_u32 v10, s87, 10, v9
	s_cselect_b32 s20, s4, 0x29ecc000
	s_add_u32 s12, s42, 0x2000
	v_sub_u32_e32 v6, v164, v0
	v_ashrrev_i32_e32 v0, 6, v10
	s_addc_u32 s13, s43, 0
	v_and_b32_e32 v0, 0xffffff00, v0
	s_add_u32 s16, s42, 0x2af4c000
	v_ashrrev_i32_e32 v1, 31, v0
	s_addc_u32 s17, s43, 0
	v_lshlrev_b64 v[0:1], 10, v[0:1]
	v_lshl_add_u64 v[0:1], s[16:17], 0, v[0:1]
	v_and_b32_e32 v98, 0x3ff0, v10
	v_mov_b32_e32 v99, 0
	v_add_u32_e32 v11, 0x2000, v10
	v_lshl_add_u64 v[100:101], v[0:1], 0, v[98:99]
	v_ashrrev_i32_e32 v0, 6, v11
	v_and_b32_e32 v0, 0xffffff00, v0
	v_ashrrev_i32_e32 v1, 31, v0
	v_lshlrev_b64 v[0:1], 10, v[0:1]
	v_lshl_add_u64 v[0:1], s[16:17], 0, v[0:1]
	v_and_b32_e32 v2, 0x3ff0, v11
	v_mov_b32_e32 v3, v99
	v_add_u32_e32 v12, 0x4000, v10
	v_lshl_add_u64 v[102:103], v[0:1], 0, v[2:3]
	v_ashrrev_i32_e32 v0, 6, v12
	v_and_b32_e32 v0, 0xffffff00, v0
	v_ashrrev_i32_e32 v1, 31, v0
	v_lshlrev_b64 v[0:1], 10, v[0:1]
	v_lshl_add_u64 v[0:1], s[16:17], 0, v[0:1]
	v_add_u32_e32 v13, 0x6000, v10
	v_lshl_add_u64 v[104:105], v[0:1], 0, v[98:99]
	v_ashrrev_i32_e32 v0, 6, v13
	v_and_b32_e32 v0, 0xffffff00, v0
	v_ashrrev_i32_e32 v1, 31, v0
	v_lshlrev_b64 v[0:1], 10, v[0:1]
	v_lshl_add_u64 v[0:1], s[16:17], 0, v[0:1]
	v_and_b32_e32 v4, 0x3ff0, v13
	v_mov_b32_e32 v5, v99
	s_mul_i32 s7, s87, 0x2400
	v_lshl_add_u64 v[106:107], v[0:1], 0, v[4:5]
	v_ashrrev_i32_e32 v0, 10, v10
	s_add_i32 s24, s7, 0
	s_add_i32 s7, 0, 0x12040
	v_and_b32_e32 v175, -16, v0
	v_ashrrev_i32_e32 v0, 10, v11
	v_add_u32_e32 v169, s7, v10
	s_add_i32 s7, s7, s18
	v_and_b32_e32 v176, -16, v0
	v_ashrrev_i32_e32 v0, 10, v12
	v_ashrrev_i32_e32 v7, 5, v164
	v_lshl_add_u64 v[108:109], s[16:17], 0, v[98:99]
	v_lshl_add_u64 v[110:111], s[16:17], 0, v[2:3]
	v_and_b32_e32 v177, -16, v0
	v_ashrrev_i32_e32 v0, 10, v13
	v_lshl_add_u64 v[112:113], s[16:17], 0, v[4:5]
	s_add_u32 s16, s42, 0x2afd0000
	v_and_b32_e32 v178, -16, v0
	s_addc_u32 s17, s43, 0
	v_lshlrev_b32_e32 v114, 2, v7
	v_add_u32_e32 v0, 1, v164
	v_add_u32_e32 v171, s7, v9
	v_and_b32_e32 v9, 63, v0
	v_lshl_add_u32 v0, s6, 6, v114
	s_add_u32 s6, s42, s14
	v_ashrrev_i32_e32 v115, 31, v114
	s_addc_u32 s7, s43, s15
	v_lshlrev_b64 v[2:3], 1, v[114:115]
	v_and_b32_e32 v167, 31, v164
	v_lshl_add_u64 v[4:5], s[6:7], 0, v[2:3]
	s_mov_b64 s[6:7], 0x2afcc000
	v_lshl_add_u64 v[4:5], v[4:5], 0, s[6:7]
	v_lshlrev_b32_e32 v98, 7, v167
	v_lshl_add_u64 v[124:125], v[4:5], 0, v[98:99]
	v_or_b32_e32 v98, 0x1000, v98
	v_lshlrev_b32_e32 v96, 4, v6
	v_lshlrev_b32_e32 v170, 3, v6
	v_add_u32_e32 v6, 8, v0
	v_lshl_add_u64 v[126:127], v[4:5], 0, v[98:99]
	v_add_u32_e32 v4, 32, v0
	v_lshlrev_b32_e32 v173, 4, v7
	v_ashrrev_i32_e32 v7, 31, v6
	v_ashrrev_i32_e32 v5, 31, v4
	v_lshl_add_u64 v[118:119], v[6:7], 2, s[16:17]
	v_add_u32_e32 v6, 16, v0
	v_lshl_add_u64 v[130:131], v[4:5], 2, s[16:17]
	v_add_u32_e32 v4, 40, v0
	v_ashrrev_i32_e32 v1, 31, v0
	v_ashrrev_i32_e32 v7, 31, v6
	v_ashrrev_i32_e32 v5, 31, v4
	s_add_u32 s14, s42, s19
	v_lshl_add_u64 v[116:117], v[0:1], 2, s[16:17]
	v_lshl_add_u64 v[120:121], v[6:7], 2, s[16:17]
	v_add_u32_e32 v6, 24, v0
	v_lshl_add_u64 v[132:133], v[4:5], 2, s[16:17]
	v_add_u32_e32 v4, 48, v0
	v_add_u32_e32 v0, 56, v0
	s_addc_u32 s15, s43, 0
	v_ashrrev_i32_e32 v1, 31, v0
	s_add_u32 s26, s42, 0x8300000
	v_lshl_add_u64 v[136:137], v[0:1], 2, s[16:17]
	v_lshl_add_u64 v[142:143], s[14:15], 0, v[2:3]
	v_lshrrev_b32_e32 v0, 29, v8
	s_addc_u32 s27, s43, 0
	s_lshl_b64 s[14:15], s[8:9], 1
	v_ashrrev_i32_e32 v7, 31, v6
	v_ashrrev_i32_e32 v5, 31, v4
	v_add_u32_e32 v0, v164, v0
	s_add_u32 s14, s26, s14
	v_lshl_add_u64 v[122:123], v[6:7], 2, s[16:17]
	v_lshl_add_u64 v[134:135], v[4:5], 2, s[16:17]
	v_ashrrev_i32_e32 v179, 3, v0
	s_addc_u32 s15, s27, s15
	s_lshl_b32 s16, s2, 7
	v_and_b32_e32 v0, 0xffffff8, v0
	s_add_u32 s18, s14, s16
	v_sub_u32_e32 v0, v164, v0
	s_addc_u32 s19, s15, 0
	v_lshlrev_b32_e32 v144, 4, v0
	v_mbcnt_hi_u32_b32 v228, -1, v166
	v_lshl_add_u32 v165, s87, 6, v164
	s_movk_i32 s21, 0x90
	s_mov_b64 s[6:7], 0x60
	v_ashrrev_i32_e32 v145, 31, v144
	s_add_u32 s25, s42, s20
	v_and_or_b32 v0, v228, 64, v9
	s_mov_b32 s11, 0
	v_cmp_eq_u32_e64 s[4:5], 0, v165
	v_ashrrev_i32_e32 v97, 31, v96
	v_mul_u32_u24_e32 v172, 0x90, v167
	v_mul_lo_u32 v174, v168, s21
	v_lshl_add_u64 v[128:129], v[126:127], 0, 32
	v_lshl_add_u64 v[138:139], v[126:127], 0, 64
	v_lshl_add_u64 v[140:141], v[126:127], 0, s[6:7]
	v_cmp_ne_u32_e64 s[6:7], 31, v167
	v_mul_lo_u32 v180, v179, s21
	s_addc_u32 s28, s43, 0
	s_add_i32 s29, 0, 0x12000
	s_movk_i32 s30, 35
	s_mov_b32 s100, 0
	s_mov_b32 s101, 0
	s_movk_i32 s31, 0x1ff
	s_lshl_b64 s[14:15], s[8:9], 2
	s_lshl_b32 s16, s10, 2
	s_movk_i32 s33, 0x200
	s_movk_i32 s34, 0x1fe
	s_movk_i32 s35, 0xff
	s_movk_i32 s36, 0x100
	s_movk_i32 s37, 0xfe
	v_lshlrev_b32_e32 v166, 2, v0
	v_mov_b32_e32 v181, 0xc0135761
	v_lshl_add_u64 v[146:147], s[18:19], 0, v[144:145]
	s_branch .LBB0_690
.Lcmp_pass_exit:
	s_cmp_lg_u32 s100, 0
	s_cbranch_scc1 .LBB0_758
	s_cmpk_ge_u32 s72, 96
	s_cbranch_scc1 .LBB0_758
	s_mov_b32 s100, 1
	s_mov_b32 s101, 36
	s_movk_i32 s30, 0x243
	s_add_u32 s12, s12, 0x100
	s_addc_u32 s13, s13, 0
	s_branch .LBB0_690

.LBB0_693:
	s_or_b64 exec, exec, s[18:19]
	s_waitcnt vmcnt(0)
	v_readfirstlane_b32 s10, v1
	v_mov_b32_e32 v1, s29
	s_nop 0
	v_add_u32_e32 v0, s10, v0
	v_add_u32_e32 v0, s101, v0
	ds_write_b32 v1, v0

.LBB0_767:
	s_or_b64 exec, exec, s[10:11]
	s_waitcnt vmcnt(0)
	v_readfirstlane_b32 s2, v2
	s_nop 1
	v_add_u32_e32 v0, s2, v0
	v_add_u32_e32 v2, 16, v0
	v_subrev_u32_e32 v3, 72, v0
	v_cmp_gt_u32_e32 vcc, 88, v0
	s_nop 1
	v_cndmask_b32_e32 v3, v0, v3, vcc
	v_cmp_gt_u32_e32 vcc, 72, v0
	s_nop 1
	v_cndmask_b32_e32 v0, v3, v2, vcc
	v_cmp_gt_i32_e32 vcc, s93, v0
	s_and_saveexec_b64 s[14:15], vcc
	s_cbranch_execz .LBB0_789
	v_cmp_gt_i32_e32 vcc, 16, v0
	v_cmp_lt_i32_e64 s[10:11], 15, v0
	v_lshlrev_b32_e32 v3, 3, v0
	s_and_saveexec_b64 s[2:3], s[10:11]
	s_xor_b64 s[10:11], exec, s[2:3]
	v_and_or_b32 v2, v3, 8, s97
	v_lshrrev_b32_e32 v2, 2, v2
	s_andn2_saveexec_b64 s[10:11], s[10:11]
	v_or_b32_e32 v2, s97, v3
	v_ashrrev_i32_e32 v2, 2, v2
	s_or_b64 exec, exec, s[10:11]
	v_add_u32_e32 v3, 4, v2
	v_cndmask_b32_e32 v4, v2, v3, vcc
	v_lshlrev_b64 v[2:3], v4, 1
	v_and_b32_e32 v7, v3, v117
	v_and_b32_e32 v6, v2, v116
	v_cmp_eq_u64_e64 s[10:11], 0, v[6:7]
	s_and_saveexec_b64 s[16:17], s[10:11]
	s_cbranch_execz .LBB0_788
	v_lshlrev_b32_e32 v4, 6, v4
	v_readlane_b32 s2, v254, 27
	v_ashrrev_i32_e32 v5, 31, v4
	v_readlane_b32 s3, v254, 28
	v_cndmask_b32_e64 v6, 9, 17, vcc
	s_mov_b64 s[10:11], 0
	v_lshl_add_u64 v[4:5], v[4:5], 2, s[2:3]
	s_mov_b32 s2, 0x400001
	s_branch .LBB0_779

.LBB0_1935:
	s_or_b64 exec, exec, s[16:17]
	v_and_b32_e32 v128, 64, v228
	s_waitcnt lgkmcnt(0)
	s_barrier
	v_or_b32_e32 v129, v241, v128
	v_or_b32_e32 v128, v242, v128
	v_lshlrev_b32_e32 v253, 2, v129
	v_lshlrev_b32_e32 v236, 2, v128
	ds_read_b128 v[148:151], v245
	ds_read_b128 v[132:135], v245 offset:512
	ds_read_b128 v[144:147], v245 offset:1024
	ds_read_b128 v[128:131], v245 offset:1536
	ds_read_b128 v[188:191], v246 offset:1024
	ds_read_b128 v[194:197], v246 offset:512
	ds_read_b128 v[198:201], v246
	ds_read_b128 v[152:155], v245 offset:2048
	ds_read_b128 v[136:139], v245 offset:2560
	ds_read_b128 v[156:159], v245 offset:3072
	ds_read_b128 v[140:143], v245 offset:3584
	ds_read_b128 v[208:211], v246 offset:1536
	s_waitcnt lgkmcnt(5)
	v_cndmask_b32_e64 v160, v188, v198, s[12:13]
	v_cndmask_b32_e64 v162, v189, v199, s[12:13]
	v_cndmask_b32_e64 v163, v190, v200, s[12:13]
	v_cndmask_b32_e64 v164, v191, v201, s[12:13]
	v_cndmask_b32_e64 v164, v127, v164, s[8:9]
	v_cndmask_b32_e64 v163, v126, v163, s[8:9]
	v_cndmask_b32_e64 v162, v125, v162, s[8:9]
	v_cndmask_b32_e64 v160, v124, v160, s[8:9]
	v_cndmask_b32_e64 v165, v127, v191, s[10:11]
	v_cndmask_b32_e64 v168, v126, v190, s[10:11]
	v_cndmask_b32_e64 v169, v125, v189, s[10:11]
	v_cndmask_b32_e64 v170, v124, v188, s[10:11]
	v_mov_b32_dpp v202, v160 row_ror:2 row_mask:0xf bank_mask:0xf
	v_mov_b32_dpp v203, v162 row_ror:2 row_mask:0xf bank_mask:0xf
	v_mov_b32_dpp v206, v163 row_ror:2 row_mask:0xf bank_mask:0xf
	v_mov_b32_dpp v207, v164 row_ror:2 row_mask:0xf bank_mask:0xf
	s_waitcnt lgkmcnt(0)
	v_cndmask_b32_e64 v160, v208, v194, s[12:13]
	v_cndmask_b32_e64 v162, v209, v195, s[12:13]
	v_cndmask_b32_e64 v163, v210, v196, s[12:13]
	v_cndmask_b32_e64 v164, v211, v197, s[12:13]
	v_mov_b32_dpp v192, v170 row_ror:1 row_mask:0xf bank_mask:0xf
	v_mov_b32_dpp v193, v169 row_ror:1 row_mask:0xf bank_mask:0xf
	v_mov_b32_dpp v198, v168 row_ror:1 row_mask:0xf bank_mask:0xf
	v_mov_b32_dpp v199, v165 row_ror:1 row_mask:0xf bank_mask:0xf
	v_cndmask_b32_e64 v165, v119, v211, s[10:11]
	v_cndmask_b32_e64 v168, v118, v210, s[10:11]
	v_cndmask_b32_e64 v169, v117, v209, s[10:11]
	v_cndmask_b32_e64 v170, v116, v208, s[10:11]
	v_cndmask_b32_e64 v164, v119, v164, s[8:9]
	v_cndmask_b32_e64 v163, v118, v163, s[8:9]
	v_cndmask_b32_e64 v162, v117, v162, s[8:9]
	v_cndmask_b32_e64 v160, v116, v160, s[8:9]
	v_mov_b32_dpp v190, v170 row_ror:1 row_mask:0xf bank_mask:0xf
	v_mov_b32_dpp v191, v169 row_ror:1 row_mask:0xf bank_mask:0xf
	v_mov_b32_dpp v196, v168 row_ror:1 row_mask:0xf bank_mask:0xf
	v_mov_b32_dpp v197, v165 row_ror:1 row_mask:0xf bank_mask:0xf
	v_mov_b32_dpp v200, v160 row_ror:2 row_mask:0xf bank_mask:0xf
	v_mov_b32_dpp v201, v162 row_ror:2 row_mask:0xf bank_mask:0xf
	v_mov_b32_dpp v204, v163 row_ror:2 row_mask:0xf bank_mask:0xf
	v_mov_b32_dpp v205, v164 row_ror:2 row_mask:0xf bank_mask:0xf
	v_lshl_add_u32 v194, s72, 8, v237
	v_ashrrev_i32_e32 v187, 31, v186
	v_lshl_add_u64 v[188:189], v[186:187], 1, s[58:59]
	v_ashrrev_i32_e32 v195, 31, v194
	s_and_saveexec_b64 s[16:17], s[60:61]
	s_cbranch_execz .LBB0_1937
	s_waitcnt lgkmcnt(0)
	v_pk_fma_f32 v[164:165], v[148:149], v[202:203], v[156:157]
	s_waitcnt lgkmcnt(0)
	v_pk_fma_f32 v[162:163], v[150:151], v[206:207], v[158:159]
	s_waitcnt lgkmcnt(0)
	v_pk_fma_f32 v[164:165], v[144:145], v[192:193], v[164:165]
	s_waitcnt lgkmcnt(0)
	v_pk_fma_f32 v[162:163], v[146:147], v[198:199], v[162:163]
	v_pk_fma_f32 v[164:165], v[124:125], v[152:153], v[164:165]
	v_pk_fma_f32 v[162:163], v[126:127], v[154:155], v[162:163]
	v_mul_f32_e32 v160, v164, v164
	v_fmamk_f32 v160, v160, 0xbdd2d3e7, v233
	v_mul_f32_e32 v185, v165, v165
	v_mul_f32_e32 v160, v164, v160
	v_fmamk_f32 v185, v185, 0xbdd2d3e7, v233
	v_exp_f32_e32 v160, v160
	v_mul_f32_e32 v185, v165, v185
	v_exp_f32_e32 v185, v185
	s_waitcnt lgkmcnt(0)
	v_pk_fma_f32 v[170:171], v[132:133], v[200:201], v[140:141]
	v_add_f32_e32 v160, 1.0, v160
	v_pk_fma_f32 v[170:171], v[128:129], v[190:191], v[170:171]
	v_rcp_f32_e32 v190, v160
	v_add_f32_e32 v160, 1.0, v185
	v_mul_f32_e32 v185, v162, v162
	v_fmamk_f32 v185, v185, 0xbdd2d3e7, v233
	v_mul_f32_e32 v191, v163, v163
	v_mul_f32_e32 v185, v162, v185
	v_fmamk_f32 v191, v191, 0xbdd2d3e7, v233
	v_exp_f32_e32 v185, v185
	v_mul_f32_e32 v191, v163, v191
	v_exp_f32_e32 v193, v191
	v_rcp_f32_e32 v191, v160
	v_add_f32_e32 v160, 1.0, v185
	v_rcp_f32_e32 v192, v160
	v_add_f32_e32 v160, 1.0, v193
	v_rcp_f32_e32 v193, v160
	s_waitcnt lgkmcnt(0)
	v_pk_fma_f32 v[168:169], v[134:135], v[204:205], v[142:143]
	v_pk_fma_f32 v[170:171], v[116:117], v[136:137], v[170:171]
	v_pk_fma_f32 v[168:169], v[130:131], v[196:197], v[168:169]
	v_pk_mul_f32 v[164:165], v[164:165], v[190:191]
	v_pk_fma_f32 v[168:169], v[118:119], v[138:139], v[168:169]
	v_pk_mul_f32 v[162:163], v[162:163], v[192:193]
	v_pk_mul_f32 v[164:165], v[164:165], v[170:171]
	v_pk_mul_f32 v[162:163], v[162:163], v[168:169]
	v_lshlrev_b64 v[168:169], 13, v[194:195]
	v_lshl_add_u64 v[168:169], v[188:189], 0, v[168:169]
	v_cvt_pk_bf16_f32 v164, v164, v165
	v_cvt_pk_bf16_f32 v165, v162, v163
	global_store_dwordx2 v[168:169], v[164:165], off
.LBB0_1937:
	s_or_b64 exec, exec, s[16:17]
	v_cndmask_b32_e64 v160, v111, v127, s[10:11]
	v_cndmask_b32_e64 v169, v109, v125, s[8:9]
	v_cndmask_b32_e64 v168, v108, v124, s[8:9]
	v_cndmask_b32_e64 v163, v109, v125, s[10:11]
	v_cndmask_b32_e64 v162, v108, v124, s[10:11]
	v_mov_b32_dpp v165, v160 row_ror:1 row_mask:0xf bank_mask:0xf
	v_cndmask_b32_e64 v160, v111, v127, s[8:9]
	v_cndmask_b32_e64 v170, v110, v126, s[8:9]
	v_mov_b32_dpp v168, v168 row_ror:2 row_mask:0xf bank_mask:0xf
	v_mov_b32_dpp v169, v169 row_ror:2 row_mask:0xf bank_mask:0xf
	v_cndmask_b32_e64 v164, v110, v126, s[10:11]
	v_mov_b32_dpp v162, v162 row_ror:1 row_mask:0xf bank_mask:0xf
	v_mov_b32_dpp v163, v163 row_ror:1 row_mask:0xf bank_mask:0xf
	v_mov_b32_dpp v170, v170 row_ror:2 row_mask:0xf bank_mask:0xf
	v_mov_b32_dpp v171, v160 row_ror:2 row_mask:0xf bank_mask:0xf
	v_mov_b32_dpp v164, v164 row_ror:1 row_mask:0xf bank_mask:0xf
	s_waitcnt lgkmcnt(0)
	v_pk_fma_f32 v[168:169], v[148:149], v[168:169], v[156:157]
	v_cndmask_b32_e64 v160, v103, v119, s[10:11]
	s_waitcnt lgkmcnt(0)
	v_pk_fma_f32 v[162:163], v[144:145], v[162:163], v[168:169]
	s_waitcnt lgkmcnt(0)
	v_pk_fma_f32 v[170:171], v[150:151], v[170:171], v[158:159]
	v_pk_fma_f32 v[162:163], v[108:109], v[152:153], v[162:163]
	s_waitcnt lgkmcnt(0)
	v_pk_fma_f32 v[164:165], v[146:147], v[164:165], v[170:171]
	v_mov_b32_dpp v171, v160 row_ror:1 row_mask:0xf bank_mask:0xf
	v_cndmask_b32_e64 v160, v103, v119, s[8:9]
	s_nop 1
	v_mov_b32_dpp v193, v160 row_ror:2 row_mask:0xf bank_mask:0xf
	v_mul_f32_e32 v160, v162, v162
	v_cndmask_b32_e64 v185, v102, v118, s[8:9]
	v_fmamk_f32 v160, v160, 0xbdd2d3e7, v233
	v_cndmask_b32_e64 v170, v102, v118, s[10:11]
	v_mov_b32_dpp v192, v185 row_ror:2 row_mask:0xf bank_mask:0xf
	v_mul_f32_e32 v160, v162, v160
	v_mov_b32_dpp v170, v170 row_ror:1 row_mask:0xf bank_mask:0xf
	v_exp_f32_e32 v160, v160
	v_pk_fma_f32 v[164:165], v[110:111], v[154:155], v[164:165]
	s_waitcnt lgkmcnt(0)
	v_pk_fma_f32 v[192:193], v[134:135], v[192:193], v[142:143]
	v_cndmask_b32_e64 v191, v101, v117, s[8:9]
	v_add_f32_e32 v160, 1.0, v160
	s_waitcnt lgkmcnt(0)
	v_pk_fma_f32 v[170:171], v[130:131], v[170:171], v[192:193]
	v_rcp_f32_e32 v192, v160
	v_mul_f32_e32 v160, v163, v163
	v_fmamk_f32 v160, v160, 0xbdd2d3e7, v233
	v_mul_f32_e32 v160, v163, v160
	v_exp_f32_e32 v160, v160
	v_cndmask_b32_e64 v190, v100, v116, s[8:9]
	v_cndmask_b32_e64 v169, v101, v117, s[10:11]
	v_cndmask_b32_e64 v168, v100, v116, s[10:11]
	v_add_f32_e32 v160, 1.0, v160
	v_mov_b32_dpp v190, v190 row_ror:2 row_mask:0xf bank_mask:0xf
	v_mov_b32_dpp v191, v191 row_ror:2 row_mask:0xf bank_mask:0xf
	v_rcp_f32_e32 v193, v160
	v_mul_f32_e32 v160, v164, v164
	v_mov_b32_dpp v168, v168 row_ror:1 row_mask:0xf bank_mask:0xf
	v_mov_b32_dpp v169, v169 row_ror:1 row_mask:0xf bank_mask:0xf
	v_fmamk_f32 v160, v160, 0xbdd2d3e7, v233
	v_mul_f32_e32 v160, v164, v160
	v_exp_f32_e32 v160, v160
	s_waitcnt lgkmcnt(0)
	v_pk_fma_f32 v[190:191], v[132:133], v[190:191], v[140:141]
	v_pk_mul_f32 v[162:163], v[162:163], v[192:193]
	s_waitcnt lgkmcnt(0)
	v_pk_fma_f32 v[168:169], v[128:129], v[168:169], v[190:191]
	v_add_f32_e32 v160, 1.0, v160
	v_pk_fma_f32 v[168:169], v[100:101], v[136:137], v[168:169]
	v_or_b32_e32 v190, 16, v194
	v_pk_mul_f32 v[162:163], v[162:163], v[168:169]
	v_rcp_f32_e32 v168, v160
	v_mul_f32_e32 v160, v165, v165
	v_fmamk_f32 v160, v160, 0xbdd2d3e7, v233
	v_mul_f32_e32 v160, v165, v160
	v_exp_f32_e32 v160, v160
	v_pk_fma_f32 v[170:171], v[102:103], v[138:139], v[170:171]
	v_ashrrev_i32_e32 v191, 31, v190
	v_cvt_pk_bf16_f32 v162, v162, v163
	v_add_f32_e32 v160, 1.0, v160
	v_rcp_f32_e32 v169, v160
	v_cndmask_b32_e64 v160, v95, v111, s[10:11]
	v_cndmask_b32_e64 v185, v86, v102, s[8:9]
	s_nop 1
	v_mov_b32_dpp v192, v185 row_ror:2 row_mask:0xf bank_mask:0xf
	v_pk_mul_f32 v[164:165], v[164:165], v[168:169]
	v_lshlrev_b64 v[168:169], 13, v[190:191]
	v_pk_mul_f32 v[164:165], v[164:165], v[170:171]
	v_lshl_add_u64 v[196:197], v[188:189], 0, v[168:169]
	v_cvt_pk_bf16_f32 v163, v164, v165
	v_cndmask_b32_e64 v169, v93, v109, s[8:9]
	v_cndmask_b32_e64 v168, v92, v108, s[8:9]
	global_store_dwordx2 v[196:197], v[162:163], off
	v_cndmask_b32_e64 v163, v93, v109, s[10:11]
	v_cndmask_b32_e64 v162, v92, v108, s[10:11]
	v_mov_b32_dpp v165, v160 row_ror:1 row_mask:0xf bank_mask:0xf
	v_cndmask_b32_e64 v160, v95, v111, s[8:9]
	v_cndmask_b32_e64 v170, v94, v110, s[8:9]
	v_mov_b32_dpp v168, v168 row_ror:2 row_mask:0xf bank_mask:0xf
	v_mov_b32_dpp v169, v169 row_ror:2 row_mask:0xf bank_mask:0xf
	v_cndmask_b32_e64 v164, v94, v110, s[10:11]
	v_mov_b32_dpp v162, v162 row_ror:1 row_mask:0xf bank_mask:0xf
	v_mov_b32_dpp v163, v163 row_ror:1 row_mask:0xf bank_mask:0xf
	v_mov_b32_dpp v170, v170 row_ror:2 row_mask:0xf bank_mask:0xf
	v_mov_b32_dpp v171, v160 row_ror:2 row_mask:0xf bank_mask:0xf
	v_mov_b32_dpp v164, v164 row_ror:1 row_mask:0xf bank_mask:0xf
	s_waitcnt lgkmcnt(0)
	v_pk_fma_f32 v[168:169], v[148:149], v[168:169], v[156:157]
	v_cndmask_b32_e64 v160, v87, v103, s[10:11]
	s_waitcnt lgkmcnt(0)
	v_pk_fma_f32 v[162:163], v[144:145], v[162:163], v[168:169]
	s_waitcnt lgkmcnt(0)
	v_pk_fma_f32 v[170:171], v[150:151], v[170:171], v[158:159]
	v_pk_fma_f32 v[162:163], v[92:93], v[152:153], v[162:163]
	s_waitcnt lgkmcnt(0)
	v_pk_fma_f32 v[164:165], v[146:147], v[164:165], v[170:171]
	v_mov_b32_dpp v171, v160 row_ror:1 row_mask:0xf bank_mask:0xf
	v_cndmask_b32_e64 v160, v87, v103, s[8:9]
	s_nop 1
	v_mov_b32_dpp v193, v160 row_ror:2 row_mask:0xf bank_mask:0xf
	v_mul_f32_e32 v160, v162, v162
	v_fmamk_f32 v160, v160, 0xbdd2d3e7, v233
	v_cndmask_b32_e64 v170, v86, v102, s[10:11]
	v_mul_f32_e32 v160, v162, v160
	s_nop 1
	v_mov_b32_dpp v170, v170 row_ror:1 row_mask:0xf bank_mask:0xf
	v_exp_f32_e32 v160, v160
	s_waitcnt lgkmcnt(0)
	v_pk_fma_f32 v[192:193], v[134:135], v[192:193], v[142:143]
	v_pk_fma_f32 v[164:165], v[94:95], v[154:155], v[164:165]
	v_cndmask_b32_e64 v191, v85, v101, s[8:9]
	v_add_f32_e32 v160, 1.0, v160
	s_waitcnt lgkmcnt(0)
	v_pk_fma_f32 v[170:171], v[130:131], v[170:171], v[192:193]
	v_rcp_f32_e32 v192, v160
	v_mul_f32_e32 v160, v163, v163
	v_fmamk_f32 v160, v160, 0xbdd2d3e7, v233
	v_mul_f32_e32 v160, v163, v160
	v_exp_f32_e32 v160, v160
	v_cndmask_b32_e64 v190, v84, v100, s[8:9]
	v_cndmask_b32_e64 v169, v85, v101, s[10:11]
	v_cndmask_b32_e64 v168, v84, v100, s[10:11]
	v_add_f32_e32 v160, 1.0, v160
	v_mov_b32_dpp v190, v190 row_ror:2 row_mask:0xf bank_mask:0xf
	v_mov_b32_dpp v191, v191 row_ror:2 row_mask:0xf bank_mask:0xf
	v_rcp_f32_e32 v193, v160
	v_mul_f32_e32 v160, v164, v164
	v_mov_b32_dpp v168, v168 row_ror:1 row_mask:0xf bank_mask:0xf
	v_mov_b32_dpp v169, v169 row_ror:1 row_mask:0xf bank_mask:0xf
	v_fmamk_f32 v160, v160, 0xbdd2d3e7, v233
	v_mul_f32_e32 v160, v164, v160
	v_exp_f32_e32 v160, v160
	s_waitcnt lgkmcnt(0)
	v_pk_fma_f32 v[190:191], v[132:133], v[190:191], v[140:141]
	v_pk_mul_f32 v[162:163], v[162:163], v[192:193]
	s_waitcnt lgkmcnt(0)
	v_pk_fma_f32 v[168:169], v[128:129], v[168:169], v[190:191]
	v_add_f32_e32 v160, 1.0, v160
	v_pk_fma_f32 v[168:169], v[84:85], v[136:137], v[168:169]
	v_or_b32_e32 v190, 32, v194
	v_pk_mul_f32 v[162:163], v[162:163], v[168:169]
	v_rcp_f32_e32 v168, v160
	v_mul_f32_e32 v160, v165, v165
	v_fmamk_f32 v160, v160, 0xbdd2d3e7, v233
	v_mul_f32_e32 v160, v165, v160
	v_exp_f32_e32 v160, v160
	v_pk_fma_f32 v[170:171], v[86:87], v[138:139], v[170:171]
	v_ashrrev_i32_e32 v191, 31, v190
	v_cvt_pk_bf16_f32 v162, v162, v163
	v_add_f32_e32 v160, 1.0, v160
	v_rcp_f32_e32 v169, v160
	v_cndmask_b32_e64 v160, v79, v95, s[10:11]
	v_cndmask_b32_e64 v185, v70, v86, s[8:9]
	s_nop 1
	v_mov_b32_dpp v192, v185 row_ror:2 row_mask:0xf bank_mask:0xf
	v_pk_mul_f32 v[164:165], v[164:165], v[168:169]
	v_lshlrev_b64 v[168:169], 13, v[190:191]
	v_pk_mul_f32 v[164:165], v[164:165], v[170:171]
	v_lshl_add_u64 v[198:199], v[188:189], 0, v[168:169]
	v_cvt_pk_bf16_f32 v163, v164, v165
	v_cndmask_b32_e64 v169, v77, v93, s[8:9]
	v_cndmask_b32_e64 v168, v76, v92, s[8:9]
	global_store_dwordx2 v[198:199], v[162:163], off
	v_cndmask_b32_e64 v163, v77, v93, s[10:11]
	v_cndmask_b32_e64 v162, v76, v92, s[10:11]
	v_mov_b32_dpp v165, v160 row_ror:1 row_mask:0xf bank_mask:0xf
	v_cndmask_b32_e64 v160, v79, v95, s[8:9]
	v_cndmask_b32_e64 v170, v78, v94, s[8:9]
	v_mov_b32_dpp v168, v168 row_ror:2 row_mask:0xf bank_mask:0xf
	v_mov_b32_dpp v169, v169 row_ror:2 row_mask:0xf bank_mask:0xf
	v_cndmask_b32_e64 v164, v78, v94, s[10:11]
	v_mov_b32_dpp v162, v162 row_ror:1 row_mask:0xf bank_mask:0xf
	v_mov_b32_dpp v163, v163 row_ror:1 row_mask:0xf bank_mask:0xf
	v_mov_b32_dpp v170, v170 row_ror:2 row_mask:0xf bank_mask:0xf
	v_mov_b32_dpp v171, v160 row_ror:2 row_mask:0xf bank_mask:0xf
	v_mov_b32_dpp v164, v164 row_ror:1 row_mask:0xf bank_mask:0xf
	s_waitcnt lgkmcnt(0)
	v_pk_fma_f32 v[168:169], v[148:149], v[168:169], v[156:157]
	v_cndmask_b32_e64 v160, v71, v87, s[10:11]
	s_waitcnt lgkmcnt(0)
	v_pk_fma_f32 v[162:163], v[144:145], v[162:163], v[168:169]
	s_waitcnt lgkmcnt(0)
	v_pk_fma_f32 v[170:171], v[150:151], v[170:171], v[158:159]
	v_pk_fma_f32 v[162:163], v[76:77], v[152:153], v[162:163]
	s_waitcnt lgkmcnt(0)
	v_pk_fma_f32 v[164:165], v[146:147], v[164:165], v[170:171]
	v_mov_b32_dpp v171, v160 row_ror:1 row_mask:0xf bank_mask:0xf
	v_cndmask_b32_e64 v160, v71, v87, s[8:9]
	s_nop 1
	v_mov_b32_dpp v193, v160 row_ror:2 row_mask:0xf bank_mask:0xf
	v_mul_f32_e32 v160, v162, v162
	v_fmamk_f32 v160, v160, 0xbdd2d3e7, v233
	v_cndmask_b32_e64 v170, v70, v86, s[10:11]
	v_mul_f32_e32 v160, v162, v160
	s_nop 1
	v_mov_b32_dpp v170, v170 row_ror:1 row_mask:0xf bank_mask:0xf
	v_exp_f32_e32 v160, v160
	s_waitcnt lgkmcnt(0)
	v_pk_fma_f32 v[192:193], v[134:135], v[192:193], v[142:143]
	v_pk_fma_f32 v[164:165], v[78:79], v[154:155], v[164:165]
	v_cndmask_b32_e64 v191, v69, v85, s[8:9]
	v_add_f32_e32 v160, 1.0, v160
	s_waitcnt lgkmcnt(0)
	v_pk_fma_f32 v[170:171], v[130:131], v[170:171], v[192:193]
	v_rcp_f32_e32 v192, v160
	v_mul_f32_e32 v160, v163, v163
	v_fmamk_f32 v160, v160, 0xbdd2d3e7, v233
	v_mul_f32_e32 v160, v163, v160
	v_exp_f32_e32 v160, v160
	v_cndmask_b32_e64 v190, v68, v84, s[8:9]
	v_cndmask_b32_e64 v169, v69, v85, s[10:11]
	v_cndmask_b32_e64 v168, v68, v84, s[10:11]
	v_add_f32_e32 v160, 1.0, v160
	v_mov_b32_dpp v190, v190 row_ror:2 row_mask:0xf bank_mask:0xf
	v_mov_b32_dpp v191, v191 row_ror:2 row_mask:0xf bank_mask:0xf
	v_rcp_f32_e32 v193, v160
	v_mul_f32_e32 v160, v164, v164
	v_mov_b32_dpp v168, v168 row_ror:1 row_mask:0xf bank_mask:0xf
	v_mov_b32_dpp v169, v169 row_ror:1 row_mask:0xf bank_mask:0xf
	v_fmamk_f32 v160, v160, 0xbdd2d3e7, v233
	v_mul_f32_e32 v160, v164, v160
	v_exp_f32_e32 v160, v160
	s_waitcnt lgkmcnt(0)
	v_pk_fma_f32 v[190:191], v[132:133], v[190:191], v[140:141]
	v_pk_mul_f32 v[162:163], v[162:163], v[192:193]
	s_waitcnt lgkmcnt(0)
	v_pk_fma_f32 v[168:169], v[128:129], v[168:169], v[190:191]
	v_add_f32_e32 v160, 1.0, v160
	v_pk_fma_f32 v[168:169], v[68:69], v[136:137], v[168:169]
	v_or_b32_e32 v190, 48, v194
	v_pk_mul_f32 v[162:163], v[162:163], v[168:169]
	v_rcp_f32_e32 v168, v160
	v_mul_f32_e32 v160, v165, v165
	v_fmamk_f32 v160, v160, 0xbdd2d3e7, v233
	v_mul_f32_e32 v160, v165, v160
	v_exp_f32_e32 v160, v160
	v_pk_fma_f32 v[170:171], v[70:71], v[138:139], v[170:171]
	v_ashrrev_i32_e32 v191, 31, v190
	v_cvt_pk_bf16_f32 v162, v162, v163
	v_add_f32_e32 v160, 1.0, v160
	v_rcp_f32_e32 v169, v160
	v_add_u32_e32 v192, 0x80, v194
	v_ashrrev_i32_e32 v193, 31, v192
	v_pk_mul_f32 v[164:165], v[164:165], v[168:169]
	s_nop 0
	v_pk_mul_f32 v[164:165], v[164:165], v[170:171]
	v_lshlrev_b64 v[168:169], 13, v[190:191]
	v_lshl_add_u64 v[200:201], v[188:189], 0, v[168:169]
	v_cvt_pk_bf16_f32 v163, v164, v165
	global_store_dwordx2 v[200:201], v[162:163], off
	ds_read_b128 v[202:205], v247 offset:3072
	ds_read_b128 v[214:217], v247 offset:2560
	ds_read_b128 v[218:221], v247 offset:3584
	ds_read_b128 v[206:209], v247 offset:2048
	s_waitcnt lgkmcnt(3)
	v_cndmask_b32_e64 v165, v63, v205, s[10:11]
	v_cndmask_b32_e64 v168, v62, v204, s[10:11]
	v_cndmask_b32_e64 v169, v61, v203, s[10:11]
	s_waitcnt lgkmcnt(0)
	v_cndmask_b32_e64 v160, v202, v206, s[12:13]
	v_cndmask_b32_e64 v162, v203, v207, s[12:13]
	v_cndmask_b32_e64 v163, v204, v208, s[12:13]
	v_cndmask_b32_e64 v164, v205, v209, s[12:13]
	v_cndmask_b32_e64 v164, v63, v164, s[8:9]
	v_cndmask_b32_e64 v163, v62, v163, s[8:9]
	v_cndmask_b32_e64 v162, v61, v162, s[8:9]
	v_cndmask_b32_e64 v160, v60, v160, s[8:9]
	v_cndmask_b32_e64 v170, v60, v202, s[10:11]
	s_nop 1
	v_mov_b32_dpp v208, v160 row_ror:2 row_mask:0xf bank_mask:0xf
	v_mov_b32_dpp v209, v162 row_ror:2 row_mask:0xf bank_mask:0xf
	v_mov_b32_dpp v212, v163 row_ror:2 row_mask:0xf bank_mask:0xf
	v_mov_b32_dpp v213, v164 row_ror:2 row_mask:0xf bank_mask:0xf
	v_cndmask_b32_e64 v160, v218, v214, s[12:13]
	v_cndmask_b32_e64 v162, v219, v215, s[12:13]
	v_cndmask_b32_e64 v163, v220, v216, s[12:13]
	v_cndmask_b32_e64 v164, v221, v217, s[12:13]
	v_mov_b32_dpp v190, v170 row_ror:1 row_mask:0xf bank_mask:0xf
	v_mov_b32_dpp v191, v169 row_ror:1 row_mask:0xf bank_mask:0xf
	v_mov_b32_dpp v204, v168 row_ror:1 row_mask:0xf bank_mask:0xf
	v_mov_b32_dpp v205, v165 row_ror:1 row_mask:0xf bank_mask:0xf
	v_cndmask_b32_e64 v165, v55, v221, s[10:11]
	v_cndmask_b32_e64 v168, v54, v220, s[10:11]
	v_cndmask_b32_e64 v169, v53, v219, s[10:11]
	v_cndmask_b32_e64 v170, v52, v218, s[10:11]
	v_cndmask_b32_e64 v164, v55, v164, s[8:9]
	v_cndmask_b32_e64 v163, v54, v163, s[8:9]
	v_cndmask_b32_e64 v162, v53, v162, s[8:9]
	v_cndmask_b32_e64 v160, v52, v160, s[8:9]
	v_mov_b32_dpp v202, v170 row_ror:1 row_mask:0xf bank_mask:0xf
	v_mov_b32_dpp v203, v169 row_ror:1 row_mask:0xf bank_mask:0xf
	v_mov_b32_dpp v206, v168 row_ror:1 row_mask:0xf bank_mask:0xf
	v_mov_b32_dpp v207, v165 row_ror:1 row_mask:0xf bank_mask:0xf
	v_mov_b32_dpp v210, v160 row_ror:2 row_mask:0xf bank_mask:0xf
	v_mov_b32_dpp v211, v162 row_ror:2 row_mask:0xf bank_mask:0xf
	v_mov_b32_dpp v214, v163 row_ror:2 row_mask:0xf bank_mask:0xf
	v_mov_b32_dpp v215, v164 row_ror:2 row_mask:0xf bank_mask:0xf
	s_and_saveexec_b64 s[16:17], s[62:63]
	s_cbranch_execz .LBB0_1939
	s_waitcnt lgkmcnt(0)
	v_pk_fma_f32 v[164:165], v[148:149], v[208:209], v[156:157]
	s_waitcnt lgkmcnt(0)
	v_pk_fma_f32 v[162:163], v[150:151], v[212:213], v[158:159]
	s_waitcnt lgkmcnt(0)
	v_pk_fma_f32 v[164:165], v[144:145], v[190:191], v[164:165]
	s_waitcnt lgkmcnt(0)
	v_pk_fma_f32 v[162:163], v[146:147], v[204:205], v[162:163]
	v_pk_fma_f32 v[164:165], v[60:61], v[152:153], v[164:165]
	v_pk_fma_f32 v[162:163], v[62:63], v[154:155], v[162:163]
	v_mul_f32_e32 v160, v164, v164
	v_fmamk_f32 v160, v160, 0xbdd2d3e7, v233
	v_mul_f32_e32 v185, v165, v165
	v_mul_f32_e32 v160, v164, v160
	v_fmamk_f32 v185, v185, 0xbdd2d3e7, v233
	v_exp_f32_e32 v160, v160
	v_mul_f32_e32 v185, v165, v185
	v_exp_f32_e32 v185, v185
	v_mul_f32_e32 v191, v163, v163
	v_add_f32_e32 v160, 1.0, v160
	v_rcp_f32_e32 v190, v160
	v_add_f32_e32 v160, 1.0, v185
	v_mul_f32_e32 v185, v162, v162
	v_fmamk_f32 v185, v185, 0xbdd2d3e7, v233
	v_mul_f32_e32 v185, v162, v185
	v_fmamk_f32 v191, v191, 0xbdd2d3e7, v233
	s_waitcnt lgkmcnt(0)
	v_pk_fma_f32 v[170:171], v[132:133], v[210:211], v[140:141]
	v_exp_f32_e32 v185, v185
	v_mul_f32_e32 v191, v163, v191
	v_pk_fma_f32 v[170:171], v[128:129], v[202:203], v[170:171]
	v_exp_f32_e32 v203, v191
	v_rcp_f32_e32 v191, v160
	v_add_f32_e32 v160, 1.0, v185
	v_rcp_f32_e32 v202, v160
	v_add_f32_e32 v160, 1.0, v203
	v_rcp_f32_e32 v203, v160
	s_waitcnt lgkmcnt(0)
	v_pk_fma_f32 v[168:169], v[134:135], v[214:215], v[142:143]
	v_pk_fma_f32 v[170:171], v[52:53], v[136:137], v[170:171]
	v_pk_fma_f32 v[168:169], v[130:131], v[206:207], v[168:169]
	v_pk_mul_f32 v[164:165], v[164:165], v[190:191]
	v_pk_fma_f32 v[168:169], v[54:55], v[138:139], v[168:169]
	v_pk_mul_f32 v[162:163], v[162:163], v[202:203]
	v_pk_mul_f32 v[164:165], v[164:165], v[170:171]
	v_pk_mul_f32 v[162:163], v[162:163], v[168:169]
	v_lshlrev_b64 v[168:169], 13, v[192:193]
	v_lshl_add_u64 v[168:169], v[188:189], 0, v[168:169]
	v_cvt_pk_bf16_f32 v164, v164, v165
	v_cvt_pk_bf16_f32 v165, v162, v163
	global_store_dwordx2 v[168:169], v[164:165], off
.LBB0_1939:
	s_or_b64 exec, exec, s[16:17]
	v_cndmask_b32_e64 v160, v47, v63, s[10:11]
	v_cndmask_b32_e64 v169, v45, v61, s[8:9]
	v_cndmask_b32_e64 v168, v44, v60, s[8:9]
	v_cndmask_b32_e64 v163, v45, v61, s[10:11]
	v_cndmask_b32_e64 v162, v44, v60, s[10:11]
	v_mov_b32_dpp v165, v160 row_ror:1 row_mask:0xf bank_mask:0xf
	v_cndmask_b32_e64 v160, v47, v63, s[8:9]
	v_cndmask_b32_e64 v170, v46, v62, s[8:9]
	v_mov_b32_dpp v168, v168 row_ror:2 row_mask:0xf bank_mask:0xf
	v_mov_b32_dpp v169, v169 row_ror:2 row_mask:0xf bank_mask:0xf
	v_cndmask_b32_e64 v164, v46, v62, s[10:11]
	v_mov_b32_dpp v162, v162 row_ror:1 row_mask:0xf bank_mask:0xf
	v_mov_b32_dpp v163, v163 row_ror:1 row_mask:0xf bank_mask:0xf
	v_mov_b32_dpp v170, v170 row_ror:2 row_mask:0xf bank_mask:0xf
	v_mov_b32_dpp v171, v160 row_ror:2 row_mask:0xf bank_mask:0xf
	v_mov_b32_dpp v164, v164 row_ror:1 row_mask:0xf bank_mask:0xf
	s_ashr_i32 s73, s72, 31
	s_waitcnt lgkmcnt(0)
	v_pk_fma_f32 v[168:169], v[148:149], v[168:169], v[156:157]
	s_lshl_b64 s[16:17], s[72:73], 16
	s_waitcnt lgkmcnt(0)
	v_pk_fma_f32 v[170:171], v[150:151], v[170:171], v[158:159]
	v_pk_fma_f32 v[162:163], v[144:145], v[162:163], v[168:169]
	v_cndmask_b32_e64 v160, v39, v55, s[10:11]
	s_add_u32 s16, s33, s16
	s_waitcnt lgkmcnt(0)
	v_pk_fma_f32 v[164:165], v[146:147], v[164:165], v[170:171]
	v_pk_fma_f32 v[162:163], v[44:45], v[152:153], v[162:163]
	v_mov_b32_dpp v171, v160 row_ror:1 row_mask:0xf bank_mask:0xf
	v_cndmask_b32_e64 v160, v39, v55, s[8:9]
	s_addc_u32 s17, s2, s17
	v_mov_b32_e32 v185, v161
	v_mov_b32_dpp v205, v160 row_ror:2 row_mask:0xf bank_mask:0xf
	v_mul_f32_e32 v160, v162, v162
	v_lshl_add_u64 v[190:191], s[16:17], 0, v[184:185]
	v_cndmask_b32_e64 v185, v38, v54, s[8:9]
	v_fmamk_f32 v160, v160, 0xbdd2d3e7, v233
	v_cndmask_b32_e64 v170, v38, v54, s[10:11]
	v_mov_b32_dpp v204, v185 row_ror:2 row_mask:0xf bank_mask:0xf
	v_mul_f32_e32 v160, v162, v160
	v_mov_b32_dpp v170, v170 row_ror:1 row_mask:0xf bank_mask:0xf
	v_exp_f32_e32 v160, v160
	v_pk_fma_f32 v[164:165], v[46:47], v[154:155], v[164:165]
	s_waitcnt lgkmcnt(0)
	v_pk_fma_f32 v[204:205], v[134:135], v[204:205], v[142:143]
	v_cndmask_b32_e64 v203, v37, v53, s[8:9]
	v_add_f32_e32 v160, 1.0, v160
	s_waitcnt lgkmcnt(0)
	v_pk_fma_f32 v[170:171], v[130:131], v[170:171], v[204:205]
	v_rcp_f32_e32 v204, v160
	v_mul_f32_e32 v160, v163, v163
	v_fmamk_f32 v160, v160, 0xbdd2d3e7, v233
	v_mul_f32_e32 v160, v163, v160
	v_exp_f32_e32 v160, v160
	v_cndmask_b32_e64 v202, v36, v52, s[8:9]
	v_cndmask_b32_e64 v169, v37, v53, s[10:11]
	v_cndmask_b32_e64 v168, v36, v52, s[10:11]
	v_add_f32_e32 v160, 1.0, v160
	v_mov_b32_dpp v202, v202 row_ror:2 row_mask:0xf bank_mask:0xf
	v_mov_b32_dpp v203, v203 row_ror:2 row_mask:0xf bank_mask:0xf
	v_rcp_f32_e32 v205, v160
	v_mul_f32_e32 v160, v164, v164
	v_mov_b32_dpp v168, v168 row_ror:1 row_mask:0xf bank_mask:0xf
	v_mov_b32_dpp v169, v169 row_ror:1 row_mask:0xf bank_mask:0xf
	v_fmamk_f32 v160, v160, 0xbdd2d3e7, v233
	v_mul_f32_e32 v160, v164, v160
	v_exp_f32_e32 v160, v160
	s_waitcnt lgkmcnt(0)
	v_pk_fma_f32 v[202:203], v[132:133], v[202:203], v[140:141]
	v_pk_mul_f32 v[162:163], v[162:163], v[204:205]
	s_waitcnt lgkmcnt(0)
	v_pk_fma_f32 v[168:169], v[128:129], v[168:169], v[202:203]
	v_add_f32_e32 v160, 1.0, v160
	v_pk_fma_f32 v[168:169], v[36:37], v[136:137], v[168:169]
	v_add_u32_e32 v202, 0x90, v194
	v_pk_mul_f32 v[162:163], v[162:163], v[168:169]
	v_rcp_f32_e32 v168, v160
	v_mul_f32_e32 v160, v165, v165
	v_fmamk_f32 v160, v160, 0xbdd2d3e7, v233
	v_mul_f32_e32 v160, v165, v160
	v_exp_f32_e32 v160, v160
	v_pk_fma_f32 v[170:171], v[38:39], v[138:139], v[170:171]
	v_ashrrev_i32_e32 v203, 31, v202
	v_cvt_pk_bf16_f32 v162, v162, v163
	v_add_f32_e32 v160, 1.0, v160
	v_rcp_f32_e32 v169, v160
	v_cndmask_b32_e64 v160, v31, v47, s[10:11]
	v_cndmask_b32_e64 v185, v22, v38, s[8:9]
	s_nop 1
	v_mov_b32_dpp v206, v185 row_ror:2 row_mask:0xf bank_mask:0xf
	v_pk_mul_f32 v[164:165], v[164:165], v[168:169]
	v_lshlrev_b64 v[168:169], 13, v[202:203]
	v_pk_mul_f32 v[164:165], v[164:165], v[170:171]
	v_lshl_add_u64 v[202:203], v[188:189], 0, v[168:169]
	v_cvt_pk_bf16_f32 v163, v164, v165
	v_cndmask_b32_e64 v169, v29, v45, s[8:9]
	v_cndmask_b32_e64 v168, v28, v44, s[8:9]
	global_store_dwordx2 v[202:203], v[162:163], off
	v_cndmask_b32_e64 v163, v29, v45, s[10:11]
	v_cndmask_b32_e64 v162, v28, v44, s[10:11]
	v_mov_b32_dpp v165, v160 row_ror:1 row_mask:0xf bank_mask:0xf
	v_cndmask_b32_e64 v160, v31, v47, s[8:9]
	v_cndmask_b32_e64 v170, v30, v46, s[8:9]
	v_mov_b32_dpp v168, v168 row_ror:2 row_mask:0xf bank_mask:0xf
	v_mov_b32_dpp v169, v169 row_ror:2 row_mask:0xf bank_mask:0xf
	v_cndmask_b32_e64 v164, v30, v46, s[10:11]
	v_mov_b32_dpp v162, v162 row_ror:1 row_mask:0xf bank_mask:0xf
	v_mov_b32_dpp v163, v163 row_ror:1 row_mask:0xf bank_mask:0xf
	v_mov_b32_dpp v170, v170 row_ror:2 row_mask:0xf bank_mask:0xf
	v_mov_b32_dpp v171, v160 row_ror:2 row_mask:0xf bank_mask:0xf
	v_mov_b32_dpp v164, v164 row_ror:1 row_mask:0xf bank_mask:0xf
	s_waitcnt lgkmcnt(0)
	v_pk_fma_f32 v[168:169], v[148:149], v[168:169], v[156:157]
	v_cndmask_b32_e64 v160, v23, v39, s[10:11]
	s_waitcnt lgkmcnt(0)
	v_pk_fma_f32 v[162:163], v[144:145], v[162:163], v[168:169]
	s_waitcnt lgkmcnt(0)
	v_pk_fma_f32 v[170:171], v[150:151], v[170:171], v[158:159]
	v_pk_fma_f32 v[162:163], v[28:29], v[152:153], v[162:163]
	s_waitcnt lgkmcnt(0)
	v_pk_fma_f32 v[164:165], v[146:147], v[164:165], v[170:171]
	v_mov_b32_dpp v171, v160 row_ror:1 row_mask:0xf bank_mask:0xf
	v_cndmask_b32_e64 v160, v23, v39, s[8:9]
	s_nop 1
	v_mov_b32_dpp v207, v160 row_ror:2 row_mask:0xf bank_mask:0xf
	v_mul_f32_e32 v160, v162, v162
	v_fmamk_f32 v160, v160, 0xbdd2d3e7, v233
	v_cndmask_b32_e64 v170, v22, v38, s[10:11]
	v_mul_f32_e32 v160, v162, v160
	s_nop 1
	v_mov_b32_dpp v170, v170 row_ror:1 row_mask:0xf bank_mask:0xf
	v_exp_f32_e32 v160, v160
	s_waitcnt lgkmcnt(0)
	v_pk_fma_f32 v[206:207], v[134:135], v[206:207], v[142:143]
	v_pk_fma_f32 v[164:165], v[30:31], v[154:155], v[164:165]
	v_cndmask_b32_e64 v205, v21, v37, s[8:9]
	v_add_f32_e32 v160, 1.0, v160
	s_waitcnt lgkmcnt(0)
	v_pk_fma_f32 v[170:171], v[130:131], v[170:171], v[206:207]
	v_rcp_f32_e32 v206, v160
	v_mul_f32_e32 v160, v163, v163
	v_fmamk_f32 v160, v160, 0xbdd2d3e7, v233
	v_mul_f32_e32 v160, v163, v160
	v_exp_f32_e32 v160, v160
	v_cndmask_b32_e64 v204, v20, v36, s[8:9]
	v_cndmask_b32_e64 v169, v21, v37, s[10:11]
	v_cndmask_b32_e64 v168, v20, v36, s[10:11]
	v_add_f32_e32 v160, 1.0, v160
	v_mov_b32_dpp v204, v204 row_ror:2 row_mask:0xf bank_mask:0xf
	v_mov_b32_dpp v205, v205 row_ror:2 row_mask:0xf bank_mask:0xf
	v_rcp_f32_e32 v207, v160
	v_mul_f32_e32 v160, v164, v164
	v_mov_b32_dpp v168, v168 row_ror:1 row_mask:0xf bank_mask:0xf
	v_mov_b32_dpp v169, v169 row_ror:1 row_mask:0xf bank_mask:0xf
	v_fmamk_f32 v160, v160, 0xbdd2d3e7, v233
	v_mul_f32_e32 v160, v164, v160
	v_exp_f32_e32 v160, v160
	s_waitcnt lgkmcnt(0)
	v_pk_fma_f32 v[204:205], v[132:133], v[204:205], v[140:141]
	v_pk_mul_f32 v[162:163], v[162:163], v[206:207]
	s_waitcnt lgkmcnt(0)
	v_pk_fma_f32 v[168:169], v[128:129], v[168:169], v[204:205]
	v_add_f32_e32 v160, 1.0, v160
	v_pk_fma_f32 v[168:169], v[20:21], v[136:137], v[168:169]
	v_add_u32_e32 v204, 0xa0, v194
	v_pk_mul_f32 v[162:163], v[162:163], v[168:169]
	v_rcp_f32_e32 v168, v160
	v_mul_f32_e32 v160, v165, v165
	v_fmamk_f32 v160, v160, 0xbdd2d3e7, v233
	v_mul_f32_e32 v160, v165, v160
	v_exp_f32_e32 v160, v160
	v_pk_fma_f32 v[170:171], v[22:23], v[138:139], v[170:171]
	v_ashrrev_i32_e32 v205, 31, v204
	v_cvt_pk_bf16_f32 v162, v162, v163
	v_add_f32_e32 v160, 1.0, v160
	v_rcp_f32_e32 v169, v160
	v_cndmask_b32_e64 v160, v15, v31, s[10:11]
	v_pk_mul_f32 v[164:165], v[164:165], v[168:169]
	s_nop 0
	v_pk_mul_f32 v[164:165], v[164:165], v[170:171]
	v_lshlrev_b64 v[168:169], 13, v[204:205]
	v_lshl_add_u64 v[204:205], v[188:189], 0, v[168:169]
	v_cvt_pk_bf16_f32 v163, v164, v165
	v_cndmask_b32_e64 v169, v13, v29, s[8:9]
	v_cndmask_b32_e64 v168, v12, v28, s[8:9]
	global_store_dwordx2 v[204:205], v[162:163], off
	v_cndmask_b32_e64 v163, v13, v29, s[10:11]
	v_cndmask_b32_e64 v162, v12, v28, s[10:11]
	v_mov_b32_dpp v168, v168 row_ror:2 row_mask:0xf bank_mask:0xf
	v_mov_b32_dpp v169, v169 row_ror:2 row_mask:0xf bank_mask:0xf
	v_mov_b32_dpp v162, v162 row_ror:1 row_mask:0xf bank_mask:0xf
	v_mov_b32_dpp v163, v163 row_ror:1 row_mask:0xf bank_mask:0xf
	v_mov_b32_dpp v165, v160 row_ror:1 row_mask:0xf bank_mask:0xf
	v_cndmask_b32_e64 v160, v15, v31, s[8:9]
	s_waitcnt lgkmcnt(0)
	v_pk_fma_f32 v[148:149], v[148:149], v[168:169], v[156:157]
	v_cndmask_b32_e64 v170, v14, v30, s[8:9]
	s_waitcnt lgkmcnt(0)
	v_pk_fma_f32 v[144:145], v[144:145], v[162:163], v[148:149]
	v_cndmask_b32_e64 v164, v14, v30, s[10:11]
	v_pk_fma_f32 v[144:145], v[12:13], v[152:153], v[144:145]
	v_cndmask_b32_e64 v153, v5, v21, s[8:9]
	v_cndmask_b32_e64 v152, v4, v20, s[8:9]
	v_mov_b32_dpp v170, v170 row_ror:2 row_mask:0xf bank_mask:0xf
	v_mov_b32_dpp v171, v160 row_ror:2 row_mask:0xf bank_mask:0xf
	v_cndmask_b32_e64 v149, v5, v21, s[10:11]
	v_cndmask_b32_e64 v148, v4, v20, s[10:11]
	v_mov_b32_dpp v152, v152 row_ror:2 row_mask:0xf bank_mask:0xf
	v_mov_b32_dpp v153, v153 row_ror:2 row_mask:0xf bank_mask:0xf
	v_mov_b32_dpp v164, v164 row_ror:1 row_mask:0xf bank_mask:0xf
	v_mov_b32_dpp v148, v148 row_ror:1 row_mask:0xf bank_mask:0xf
	v_mov_b32_dpp v149, v149 row_ror:1 row_mask:0xf bank_mask:0xf
	s_waitcnt lgkmcnt(0)
	v_pk_fma_f32 v[150:151], v[150:151], v[170:171], v[158:159]
	s_waitcnt lgkmcnt(0)
	v_pk_fma_f32 v[132:133], v[132:133], v[152:153], v[140:141]
	s_waitcnt lgkmcnt(0)
	v_pk_fma_f32 v[146:147], v[146:147], v[164:165], v[150:151]
	v_cndmask_b32_e64 v151, v7, v23, s[10:11]
	s_waitcnt lgkmcnt(0)
	v_pk_fma_f32 v[128:129], v[128:129], v[148:149], v[132:133]
	v_mul_f32_e32 v133, v144, v144
	v_pk_fma_f32 v[146:147], v[14:15], v[154:155], v[146:147]
	v_cndmask_b32_e64 v155, v7, v23, s[8:9]
	v_cndmask_b32_e64 v154, v6, v22, s[8:9]
	v_fmamk_f32 v133, v133, 0xbdd2d3e7, v233
	v_cndmask_b32_e64 v150, v6, v22, s[10:11]
	v_mov_b32_dpp v154, v154 row_ror:2 row_mask:0xf bank_mask:0xf
	v_mov_b32_dpp v155, v155 row_ror:2 row_mask:0xf bank_mask:0xf
	v_mul_f32_e32 v133, v144, v133
	v_mov_b32_dpp v150, v150 row_ror:1 row_mask:0xf bank_mask:0xf
	v_mov_b32_dpp v151, v151 row_ror:1 row_mask:0xf bank_mask:0xf
	v_exp_f32_e32 v133, v133
	s_waitcnt lgkmcnt(0)
	v_pk_fma_f32 v[134:135], v[134:135], v[154:155], v[142:143]
	v_pk_fma_f32 v[128:129], v[4:5], v[136:137], v[128:129]
	v_add_u32_e32 v132, 0xb0, v194
	v_add_f32_e32 v133, 1.0, v133
	s_waitcnt lgkmcnt(0)
	v_pk_fma_f32 v[130:131], v[130:131], v[150:151], v[134:135]
	v_rcp_f32_e32 v134, v133
	v_mul_f32_e32 v133, v145, v145
	v_fmamk_f32 v133, v133, 0xbdd2d3e7, v233
	v_mul_f32_e32 v133, v145, v133
	v_exp_f32_e32 v133, v133
	v_pk_fma_f32 v[130:131], v[6:7], v[138:139], v[130:131]
	v_add_f32_e32 v133, 1.0, v133
	v_rcp_f32_e32 v135, v133
	v_mul_f32_e32 v133, v146, v146
	v_fmamk_f32 v133, v133, 0xbdd2d3e7, v233
	v_mul_f32_e32 v133, v146, v133
	v_exp_f32_e32 v133, v133
	v_pk_mul_f32 v[134:135], v[144:145], v[134:135]
	v_add_f32_e32 v133, 1.0, v133
	v_pk_mul_f32 v[128:129], v[134:135], v[128:129]
	v_rcp_f32_e32 v134, v133
	v_mul_f32_e32 v133, v147, v147
	v_fmamk_f32 v133, v133, 0xbdd2d3e7, v233
	v_mul_f32_e32 v133, v147, v133
	v_exp_f32_e32 v133, v133
	v_cvt_pk_bf16_f32 v128, v128, v129
	v_add_f32_e32 v133, 1.0, v133
	v_rcp_f32_e32 v135, v133
	v_ashrrev_i32_e32 v133, 31, v132
	v_lshlrev_b64 v[132:133], 13, v[132:133]
	v_lshl_add_u64 v[210:211], v[188:189], 0, v[132:133]
	v_pk_mul_f32 v[134:135], v[146:147], v[134:135]
	s_nop 0
	v_pk_mul_f32 v[130:131], v[134:135], v[130:131]
	s_nop 0
	v_cvt_pk_bf16_f32 v129, v130, v131
	global_store_dwordx2 v[210:211], v[128:129], off
	v_lshl_add_u64 v[208:209], v[186:187], 1, v[190:191]
	s_and_saveexec_b64 s[74:75], s[34:35]
	s_cbranch_execz .LBB0_1941
	v_cvt_pk_bf16_f32 v128, v124, v125
	v_cvt_pk_bf16_f32 v129, v126, v127
	global_store_dwordx2 v[208:209], v[128:129], off

.LBB0_1949:
	s_or_b64 exec, exec, s[74:75]
	ds_read_b128 v[152:155], v245 offset:16
	ds_read_b128 v[136:139], v245 offset:528
	ds_read_b128 v[148:151], v245 offset:1040
	ds_read_b128 v[132:135], v245 offset:1552
	ds_read_b128 v[212:215], v248
	ds_read_b128 v[168:171], v250
	ds_read_b128 v[216:219], v251
	ds_read_b128 v[144:147], v245 offset:2064
	ds_read_b128 v[128:131], v245 offset:2576
	ds_read_b128 v[156:159], v245 offset:3088
	ds_read_b128 v[140:143], v245 offset:3600
	ds_read_b128 v[162:165], v249
	s_waitcnt lgkmcnt(5)
	v_cndmask_b32_e64 v185, v212, v216, s[12:13]
	v_cndmask_b32_e64 v216, v213, v217, s[12:13]
	v_cndmask_b32_e64 v217, v214, v218, s[12:13]
	v_cndmask_b32_e64 v220, v215, v219, s[12:13]
	v_cndmask_b32_e64 v213, v121, v213, s[10:11]
	v_cndmask_b32_e64 v212, v120, v212, s[10:11]
	s_waitcnt lgkmcnt(0)
	v_cndmask_b32_e64 v162, v168, v162, s[12:13]
	v_cndmask_b32_e64 v163, v169, v163, s[12:13]
	v_cndmask_b32_e64 v164, v170, v164, s[12:13]
	v_cndmask_b32_e64 v165, v171, v165, s[12:13]
	v_cndmask_b32_e64 v219, v123, v215, s[10:11]
	v_cndmask_b32_e64 v218, v122, v214, s[10:11]
	v_mov_b32_dpp v214, v212 row_ror:1 row_mask:0xf bank_mask:0xf
	v_mov_b32_dpp v215, v213 row_ror:1 row_mask:0xf bank_mask:0xf
	v_cndmask_b32_e64 v212, v123, v220, s[8:9]
	v_cndmask_b32_e64 v213, v122, v217, s[8:9]
	v_cndmask_b32_e64 v216, v121, v216, s[8:9]
	v_cndmask_b32_e64 v185, v120, v185, s[8:9]
	v_cndmask_b32_e64 v171, v115, v171, s[10:11]
	v_cndmask_b32_e64 v170, v114, v170, s[10:11]
	v_cndmask_b32_e64 v169, v113, v169, s[10:11]
	v_cndmask_b32_e64 v168, v112, v168, s[10:11]
	v_cndmask_b32_e64 v165, v115, v165, s[8:9]
	v_cndmask_b32_e64 v164, v114, v164, s[8:9]
	v_cndmask_b32_e64 v163, v113, v163, s[8:9]
	v_cndmask_b32_e64 v162, v112, v162, s[8:9]
	v_mov_b32_dpp v218, v218 row_ror:1 row_mask:0xf bank_mask:0xf
	v_mov_b32_dpp v219, v219 row_ror:1 row_mask:0xf bank_mask:0xf
	v_mov_b32_dpp v222, v185 row_ror:2 row_mask:0xf bank_mask:0xf
	v_mov_b32_dpp v223, v216 row_ror:2 row_mask:0xf bank_mask:0xf
	v_mov_b32_dpp v226, v213 row_ror:2 row_mask:0xf bank_mask:0xf
	v_mov_b32_dpp v227, v212 row_ror:2 row_mask:0xf bank_mask:0xf
	v_mov_b32_dpp v212, v168 row_ror:1 row_mask:0xf bank_mask:0xf
	v_mov_b32_dpp v213, v169 row_ror:1 row_mask:0xf bank_mask:0xf
	v_mov_b32_dpp v216, v170 row_ror:1 row_mask:0xf bank_mask:0xf
	v_mov_b32_dpp v217, v171 row_ror:1 row_mask:0xf bank_mask:0xf
	v_mov_b32_dpp v220, v162 row_ror:2 row_mask:0xf bank_mask:0xf
	v_mov_b32_dpp v221, v163 row_ror:2 row_mask:0xf bank_mask:0xf
	v_mov_b32_dpp v224, v164 row_ror:2 row_mask:0xf bank_mask:0xf
	v_mov_b32_dpp v225, v165 row_ror:2 row_mask:0xf bank_mask:0xf
	s_and_saveexec_b64 s[74:75], s[60:61]
	s_cbranch_execz .LBB0_1951
	s_waitcnt lgkmcnt(0)
	v_pk_fma_f32 v[164:165], v[152:153], v[222:223], v[156:157]
	s_waitcnt lgkmcnt(0)
	v_pk_fma_f32 v[170:171], v[136:137], v[220:221], v[140:141]
	v_pk_fma_f32 v[164:165], v[148:149], v[214:215], v[164:165]
	v_pk_fma_f32 v[170:171], v[132:133], v[212:213], v[170:171]
	v_pk_fma_f32 v[164:165], v[120:121], v[144:145], v[164:165]
	v_pk_fma_f32 v[162:163], v[154:155], v[226:227], v[158:159]
	v_mul_f32_e32 v185, v164, v164
	v_fmamk_f32 v185, v185, 0xbdd2d3e7, v233
	v_mul_f32_e32 v212, v165, v165
	v_mul_f32_e32 v185, v164, v185
	v_fmamk_f32 v212, v212, 0xbdd2d3e7, v233
	v_exp_f32_e32 v185, v185
	v_mul_f32_e32 v212, v165, v212
	v_exp_f32_e32 v213, v212
	v_pk_fma_f32 v[162:163], v[150:151], v[218:219], v[162:163]
	v_add_f32_e32 v185, 1.0, v185
	v_pk_fma_f32 v[162:163], v[122:123], v[146:147], v[162:163]
	v_rcp_f32_e32 v212, v185
	v_add_f32_e32 v185, 1.0, v213
	v_mul_f32_e32 v213, v162, v162
	v_fmamk_f32 v213, v213, 0xbdd2d3e7, v233
	v_mul_f32_e32 v213, v162, v213
	v_exp_f32_e32 v214, v213
	v_mul_f32_e32 v213, v163, v163
	v_fmamk_f32 v213, v213, 0xbdd2d3e7, v233
	v_mul_f32_e32 v213, v163, v213
	v_exp_f32_e32 v215, v213
	v_rcp_f32_e32 v213, v185
	v_add_f32_e32 v185, 1.0, v214
	v_rcp_f32_e32 v214, v185
	v_add_f32_e32 v185, 1.0, v215
	v_rcp_f32_e32 v215, v185
	s_waitcnt lgkmcnt(0)
	v_pk_fma_f32 v[168:169], v[138:139], v[224:225], v[142:143]
	v_pk_fma_f32 v[170:171], v[112:113], v[128:129], v[170:171]
	v_pk_fma_f32 v[168:169], v[134:135], v[216:217], v[168:169]
	v_pk_mul_f32 v[164:165], v[164:165], v[212:213]
	v_pk_fma_f32 v[168:169], v[114:115], v[130:131], v[168:169]
	v_pk_mul_f32 v[162:163], v[162:163], v[214:215]
	v_pk_mul_f32 v[164:165], v[164:165], v[170:171]
	v_pk_mul_f32 v[162:163], v[162:163], v[168:169]
	v_lshlrev_b64 v[168:169], 13, v[194:195]
	v_lshl_add_u64 v[168:169], v[188:189], 0, v[168:169]
	v_cvt_pk_bf16_f32 v164, v164, v165
	v_cvt_pk_bf16_f32 v165, v162, v163
	global_store_dwordx2 v[168:169], v[164:165], off offset:8
.LBB0_1951:
	s_or_b64 exec, exec, s[74:75]
	v_cndmask_b32_e64 v169, v105, v121, s[8:9]
	v_cndmask_b32_e64 v168, v104, v120, s[8:9]
	v_cndmask_b32_e64 v163, v105, v121, s[10:11]
	v_cndmask_b32_e64 v162, v104, v120, s[10:11]
	v_mov_b32_dpp v168, v168 row_ror:2 row_mask:0xf bank_mask:0xf
	v_mov_b32_dpp v169, v169 row_ror:2 row_mask:0xf bank_mask:0xf
	v_mov_b32_dpp v162, v162 row_ror:1 row_mask:0xf bank_mask:0xf
	v_mov_b32_dpp v163, v163 row_ror:1 row_mask:0xf bank_mask:0xf
	v_cndmask_b32_e64 v185, v99, v115, s[8:9]
	s_waitcnt lgkmcnt(0)
	s_nop 1
	v_mov_b32_dpp v213, v185 row_ror:2 row_mask:0xf bank_mask:0xf
	s_waitcnt lgkmcnt(0)
	v_pk_fma_f32 v[168:169], v[152:153], v[168:169], v[156:157]
	v_cndmask_b32_e64 v195, v97, v113, s[8:9]
	s_waitcnt lgkmcnt(0)
	v_pk_fma_f32 v[162:163], v[148:149], v[162:163], v[168:169]
	v_cndmask_b32_e64 v194, v96, v112, s[8:9]
	v_pk_fma_f32 v[162:163], v[104:105], v[144:145], v[162:163]
	v_cndmask_b32_e64 v169, v97, v113, s[10:11]
	v_mul_f32_e32 v185, v162, v162
	v_fmamk_f32 v185, v185, 0xbdd2d3e7, v233
	v_cndmask_b32_e64 v168, v96, v112, s[10:11]
	v_mov_b32_dpp v194, v194 row_ror:2 row_mask:0xf bank_mask:0xf
	v_mov_b32_dpp v195, v195 row_ror:2 row_mask:0xf bank_mask:0xf
	v_mul_f32_e32 v185, v162, v185
	v_mov_b32_dpp v168, v168 row_ror:1 row_mask:0xf bank_mask:0xf
	v_mov_b32_dpp v169, v169 row_ror:1 row_mask:0xf bank_mask:0xf
	v_exp_f32_e32 v185, v185
	s_waitcnt lgkmcnt(0)
	v_pk_fma_f32 v[194:195], v[136:137], v[194:195], v[140:141]
	v_cndmask_b32_e64 v171, v107, v123, s[8:9]
	v_cndmask_b32_e64 v170, v106, v122, s[8:9]
	v_add_f32_e32 v185, 1.0, v185
	s_waitcnt lgkmcnt(0)
	v_pk_fma_f32 v[168:169], v[132:133], v[168:169], v[194:195]
	v_rcp_f32_e32 v194, v185
	v_mul_f32_e32 v185, v163, v163
	v_fmamk_f32 v185, v185, 0xbdd2d3e7, v233
	v_mul_f32_e32 v185, v163, v185
	v_exp_f32_e32 v185, v185
	v_cndmask_b32_e64 v165, v107, v123, s[10:11]
	v_cndmask_b32_e64 v164, v106, v122, s[10:11]
	v_mov_b32_dpp v170, v170 row_ror:2 row_mask:0xf bank_mask:0xf
	v_mov_b32_dpp v171, v171 row_ror:2 row_mask:0xf bank_mask:0xf
	v_mov_b32_dpp v164, v164 row_ror:1 row_mask:0xf bank_mask:0xf
	v_mov_b32_dpp v165, v165 row_ror:1 row_mask:0xf bank_mask:0xf
	v_add_f32_e32 v185, 1.0, v185
	v_rcp_f32_e32 v195, v185
	s_waitcnt lgkmcnt(0)
	v_pk_fma_f32 v[170:171], v[154:155], v[170:171], v[158:159]
	v_pk_fma_f32 v[168:169], v[96:97], v[128:129], v[168:169]
	s_waitcnt lgkmcnt(0)
	v_pk_fma_f32 v[164:165], v[150:151], v[164:165], v[170:171]
	v_pk_mul_f32 v[162:163], v[162:163], v[194:195]
	v_pk_fma_f32 v[164:165], v[106:107], v[146:147], v[164:165]
	v_pk_mul_f32 v[162:163], v[162:163], v[168:169]
	v_mul_f32_e32 v168, v164, v164
	v_mul_f32_e32 v169, v165, v165
	v_fmamk_f32 v168, v168, 0xbdd2d3e7, v233
	v_fmamk_f32 v169, v169, 0xbdd2d3e7, v233
	v_mul_f32_e32 v168, v164, v168
	v_mul_f32_e32 v169, v165, v169
	v_exp_f32_e32 v168, v168
	v_exp_f32_e32 v169, v169
	v_cndmask_b32_e64 v212, v98, v114, s[8:9]
	v_cndmask_b32_e64 v171, v99, v115, s[10:11]
	v_cndmask_b32_e64 v170, v98, v114, s[10:11]
	v_mov_b32_dpp v212, v212 row_ror:2 row_mask:0xf bank_mask:0xf
	s_nop 1
	v_mov_b32_dpp v170, v170 row_ror:1 row_mask:0xf bank_mask:0xf
	v_mov_b32_dpp v171, v171 row_ror:1 row_mask:0xf bank_mask:0xf
	v_add_f32_e32 v168, 1.0, v168
	v_add_f32_e32 v169, 1.0, v169
	v_rcp_f32_e32 v168, v168
	v_rcp_f32_e32 v169, v169
	s_waitcnt lgkmcnt(0)
	v_pk_fma_f32 v[212:213], v[138:139], v[212:213], v[142:143]
	v_cvt_pk_bf16_f32 v162, v162, v163
	s_waitcnt lgkmcnt(0)
	v_pk_fma_f32 v[170:171], v[134:135], v[170:171], v[212:213]
	v_pk_mul_f32 v[164:165], v[164:165], v[168:169]
	v_pk_fma_f32 v[170:171], v[98:99], v[130:131], v[170:171]
	v_cndmask_b32_e64 v169, v89, v105, s[8:9]
	v_pk_mul_f32 v[164:165], v[164:165], v[170:171]
	v_cndmask_b32_e64 v168, v88, v104, s[8:9]
	v_cvt_pk_bf16_f32 v163, v164, v165
	global_store_dwordx2 v[196:197], v[162:163], off offset:8
	v_cndmask_b32_e64 v163, v89, v105, s[10:11]
	v_cndmask_b32_e64 v162, v88, v104, s[10:11]
	v_mov_b32_dpp v168, v168 row_ror:2 row_mask:0xf bank_mask:0xf
	v_mov_b32_dpp v169, v169 row_ror:2 row_mask:0xf bank_mask:0xf
	v_mov_b32_dpp v162, v162 row_ror:1 row_mask:0xf bank_mask:0xf
	v_mov_b32_dpp v163, v163 row_ror:1 row_mask:0xf bank_mask:0xf
	v_cndmask_b32_e64 v185, v83, v99, s[8:9]
	s_nop 1
	v_mov_b32_dpp v197, v185 row_ror:2 row_mask:0xf bank_mask:0xf
	s_waitcnt lgkmcnt(0)
	v_pk_fma_f32 v[168:169], v[152:153], v[168:169], v[156:157]
	v_cndmask_b32_e64 v195, v81, v97, s[8:9]
	s_waitcnt lgkmcnt(0)
	v_pk_fma_f32 v[162:163], v[148:149], v[162:163], v[168:169]
	v_cndmask_b32_e64 v194, v80, v96, s[8:9]
	v_pk_fma_f32 v[162:163], v[88:89], v[144:145], v[162:163]
	v_cndmask_b32_e64 v169, v81, v97, s[10:11]
	v_mul_f32_e32 v185, v162, v162
	v_fmamk_f32 v185, v185, 0xbdd2d3e7, v233
	v_cndmask_b32_e64 v168, v80, v96, s[10:11]
	v_mov_b32_dpp v194, v194 row_ror:2 row_mask:0xf bank_mask:0xf
	v_mov_b32_dpp v195, v195 row_ror:2 row_mask:0xf bank_mask:0xf
	v_mul_f32_e32 v185, v162, v185
	v_mov_b32_dpp v168, v168 row_ror:1 row_mask:0xf bank_mask:0xf
	v_mov_b32_dpp v169, v169 row_ror:1 row_mask:0xf bank_mask:0xf
	v_exp_f32_e32 v185, v185
	s_waitcnt lgkmcnt(0)
	v_pk_fma_f32 v[194:195], v[136:137], v[194:195], v[140:141]
	v_cndmask_b32_e64 v171, v91, v107, s[8:9]
	v_cndmask_b32_e64 v170, v90, v106, s[8:9]
	v_add_f32_e32 v185, 1.0, v185
	s_waitcnt lgkmcnt(0)
	v_pk_fma_f32 v[168:169], v[132:133], v[168:169], v[194:195]
	v_rcp_f32_e32 v194, v185
	v_mul_f32_e32 v185, v163, v163
	v_fmamk_f32 v185, v185, 0xbdd2d3e7, v233
	v_mul_f32_e32 v185, v163, v185
	v_exp_f32_e32 v185, v185
	v_cndmask_b32_e64 v165, v91, v107, s[10:11]
	v_cndmask_b32_e64 v164, v90, v106, s[10:11]
	v_mov_b32_dpp v170, v170 row_ror:2 row_mask:0xf bank_mask:0xf
	v_mov_b32_dpp v171, v171 row_ror:2 row_mask:0xf bank_mask:0xf
	v_mov_b32_dpp v164, v164 row_ror:1 row_mask:0xf bank_mask:0xf
	v_mov_b32_dpp v165, v165 row_ror:1 row_mask:0xf bank_mask:0xf
	v_add_f32_e32 v185, 1.0, v185
	v_rcp_f32_e32 v195, v185
	s_waitcnt lgkmcnt(0)
	v_pk_fma_f32 v[170:171], v[154:155], v[170:171], v[158:159]
	v_pk_fma_f32 v[168:169], v[80:81], v[128:129], v[168:169]
	s_waitcnt lgkmcnt(0)
	v_pk_fma_f32 v[164:165], v[150:151], v[164:165], v[170:171]
	v_pk_mul_f32 v[162:163], v[162:163], v[194:195]
	v_pk_fma_f32 v[164:165], v[90:91], v[146:147], v[164:165]
	v_pk_mul_f32 v[162:163], v[162:163], v[168:169]
	v_mul_f32_e32 v168, v164, v164
	v_mul_f32_e32 v169, v165, v165
	v_fmamk_f32 v168, v168, 0xbdd2d3e7, v233
	v_fmamk_f32 v169, v169, 0xbdd2d3e7, v233
	v_mul_f32_e32 v168, v164, v168
	v_mul_f32_e32 v169, v165, v169
	v_exp_f32_e32 v168, v168
	v_exp_f32_e32 v169, v169
	v_cndmask_b32_e64 v196, v82, v98, s[8:9]
	v_cndmask_b32_e64 v171, v83, v99, s[10:11]
	v_cndmask_b32_e64 v170, v82, v98, s[10:11]
	v_mov_b32_dpp v196, v196 row_ror:2 row_mask:0xf bank_mask:0xf
	s_nop 1
	v_mov_b32_dpp v170, v170 row_ror:1 row_mask:0xf bank_mask:0xf
	v_mov_b32_dpp v171, v171 row_ror:1 row_mask:0xf bank_mask:0xf
	v_add_f32_e32 v168, 1.0, v168
	v_add_f32_e32 v169, 1.0, v169
	v_rcp_f32_e32 v168, v168
	v_rcp_f32_e32 v169, v169
	s_waitcnt lgkmcnt(0)
	v_pk_fma_f32 v[196:197], v[138:139], v[196:197], v[142:143]
	v_cvt_pk_bf16_f32 v162, v162, v163
	s_waitcnt lgkmcnt(0)
	v_pk_fma_f32 v[170:171], v[134:135], v[170:171], v[196:197]
	v_pk_mul_f32 v[164:165], v[164:165], v[168:169]
	v_pk_fma_f32 v[170:171], v[82:83], v[130:131], v[170:171]
	v_cndmask_b32_e64 v169, v73, v89, s[8:9]
	v_pk_mul_f32 v[164:165], v[164:165], v[170:171]
	v_cndmask_b32_e64 v168, v72, v88, s[8:9]
	v_cvt_pk_bf16_f32 v163, v164, v165
	global_store_dwordx2 v[198:199], v[162:163], off offset:8
	v_cndmask_b32_e64 v163, v73, v89, s[10:11]
	v_cndmask_b32_e64 v162, v72, v88, s[10:11]
	v_mov_b32_dpp v168, v168 row_ror:2 row_mask:0xf bank_mask:0xf
	v_mov_b32_dpp v169, v169 row_ror:2 row_mask:0xf bank_mask:0xf
	v_mov_b32_dpp v162, v162 row_ror:1 row_mask:0xf bank_mask:0xf
	v_mov_b32_dpp v163, v163 row_ror:1 row_mask:0xf bank_mask:0xf
	v_cndmask_b32_e64 v185, v67, v83, s[8:9]
	s_nop 1
	v_mov_b32_dpp v197, v185 row_ror:2 row_mask:0xf bank_mask:0xf
	s_waitcnt lgkmcnt(0)
	v_pk_fma_f32 v[168:169], v[152:153], v[168:169], v[156:157]
	v_cndmask_b32_e64 v195, v65, v81, s[8:9]
	s_waitcnt lgkmcnt(0)
	v_pk_fma_f32 v[162:163], v[148:149], v[162:163], v[168:169]
	v_cndmask_b32_e64 v194, v64, v80, s[8:9]
	v_pk_fma_f32 v[162:163], v[72:73], v[144:145], v[162:163]
	v_cndmask_b32_e64 v169, v65, v81, s[10:11]
	v_mul_f32_e32 v185, v162, v162
	v_fmamk_f32 v185, v185, 0xbdd2d3e7, v233
	v_cndmask_b32_e64 v168, v64, v80, s[10:11]
	v_mov_b32_dpp v194, v194 row_ror:2 row_mask:0xf bank_mask:0xf
	v_mov_b32_dpp v195, v195 row_ror:2 row_mask:0xf bank_mask:0xf
	v_mul_f32_e32 v185, v162, v185
	v_mov_b32_dpp v168, v168 row_ror:1 row_mask:0xf bank_mask:0xf
	v_mov_b32_dpp v169, v169 row_ror:1 row_mask:0xf bank_mask:0xf
	v_exp_f32_e32 v185, v185
	s_waitcnt lgkmcnt(0)
	v_pk_fma_f32 v[194:195], v[136:137], v[194:195], v[140:141]
	v_cndmask_b32_e64 v171, v75, v91, s[8:9]
	v_cndmask_b32_e64 v170, v74, v90, s[8:9]
	v_add_f32_e32 v185, 1.0, v185
	s_waitcnt lgkmcnt(0)
	v_pk_fma_f32 v[168:169], v[132:133], v[168:169], v[194:195]
	v_rcp_f32_e32 v194, v185
	v_mul_f32_e32 v185, v163, v163
	v_fmamk_f32 v185, v185, 0xbdd2d3e7, v233
	v_mul_f32_e32 v185, v163, v185
	v_exp_f32_e32 v185, v185
	v_cndmask_b32_e64 v165, v75, v91, s[10:11]
	v_cndmask_b32_e64 v164, v74, v90, s[10:11]
	v_mov_b32_dpp v170, v170 row_ror:2 row_mask:0xf bank_mask:0xf
	v_mov_b32_dpp v171, v171 row_ror:2 row_mask:0xf bank_mask:0xf
	v_mov_b32_dpp v164, v164 row_ror:1 row_mask:0xf bank_mask:0xf
	v_mov_b32_dpp v165, v165 row_ror:1 row_mask:0xf bank_mask:0xf
	v_add_f32_e32 v185, 1.0, v185
	v_rcp_f32_e32 v195, v185
	s_waitcnt lgkmcnt(0)
	v_pk_fma_f32 v[170:171], v[154:155], v[170:171], v[158:159]
	v_pk_fma_f32 v[168:169], v[64:65], v[128:129], v[168:169]
	s_waitcnt lgkmcnt(0)
	v_pk_fma_f32 v[164:165], v[150:151], v[164:165], v[170:171]
	v_pk_mul_f32 v[162:163], v[162:163], v[194:195]
	v_pk_fma_f32 v[164:165], v[74:75], v[146:147], v[164:165]
	v_pk_mul_f32 v[162:163], v[162:163], v[168:169]
	v_mul_f32_e32 v168, v164, v164
	v_mul_f32_e32 v169, v165, v165
	v_fmamk_f32 v168, v168, 0xbdd2d3e7, v233
	v_fmamk_f32 v169, v169, 0xbdd2d3e7, v233
	v_mul_f32_e32 v168, v164, v168
	v_mul_f32_e32 v169, v165, v169
	v_exp_f32_e32 v168, v168
	v_exp_f32_e32 v169, v169
	v_cndmask_b32_e64 v196, v66, v82, s[8:9]
	v_cndmask_b32_e64 v171, v67, v83, s[10:11]
	v_cndmask_b32_e64 v170, v66, v82, s[10:11]
	v_mov_b32_dpp v196, v196 row_ror:2 row_mask:0xf bank_mask:0xf
	s_nop 1
	v_mov_b32_dpp v170, v170 row_ror:1 row_mask:0xf bank_mask:0xf
	v_mov_b32_dpp v171, v171 row_ror:1 row_mask:0xf bank_mask:0xf
	v_add_f32_e32 v168, 1.0, v168
	v_add_f32_e32 v169, 1.0, v169
	v_rcp_f32_e32 v168, v168
	v_rcp_f32_e32 v169, v169
	s_waitcnt lgkmcnt(0)
	v_pk_fma_f32 v[196:197], v[138:139], v[196:197], v[142:143]
	v_cvt_pk_bf16_f32 v162, v162, v163
	s_waitcnt lgkmcnt(0)
	v_pk_fma_f32 v[170:171], v[134:135], v[170:171], v[196:197]
	v_pk_mul_f32 v[164:165], v[164:165], v[168:169]
	v_pk_fma_f32 v[170:171], v[66:67], v[130:131], v[170:171]
	s_nop 0
	v_pk_mul_f32 v[164:165], v[164:165], v[170:171]
	s_nop 0
	v_cvt_pk_bf16_f32 v163, v164, v165
	global_store_dwordx2 v[200:201], v[162:163], off offset:8
	ds_read_b128 v[162:165], v247 offset:3088
	ds_read_b128 v[168:171], v247 offset:2576
	ds_read_b128 v[218:221], v247 offset:3600
	ds_read_b128 v[194:197], v247 offset:2064
	s_waitcnt lgkmcnt(0)
	v_cndmask_b32_e64 v185, v162, v194, s[12:13]
	v_cndmask_b32_e64 v200, v163, v195, s[12:13]
	v_cndmask_b32_e64 v196, v164, v196, s[12:13]
	v_cndmask_b32_e64 v197, v165, v197, s[12:13]
	v_cndmask_b32_e64 v165, v59, v165, s[10:11]
	v_cndmask_b32_e64 v164, v58, v164, s[10:11]
	v_cndmask_b32_e64 v163, v57, v163, s[10:11]
	v_cndmask_b32_e64 v162, v56, v162, s[10:11]
	s_nop 1
	v_mov_b32_dpp v194, v162 row_ror:1 row_mask:0xf bank_mask:0xf
	v_mov_b32_dpp v195, v163 row_ror:1 row_mask:0xf bank_mask:0xf
	v_mov_b32_dpp v198, v164 row_ror:1 row_mask:0xf bank_mask:0xf
	v_mov_b32_dpp v199, v165 row_ror:1 row_mask:0xf bank_mask:0xf
	v_cndmask_b32_e64 v162, v59, v197, s[8:9]
	v_cndmask_b32_e64 v163, v58, v196, s[8:9]
	v_cndmask_b32_e64 v164, v57, v200, s[8:9]
	v_cndmask_b32_e64 v165, v56, v185, s[8:9]
	s_nop 1
	v_mov_b32_dpp v212, v165 row_ror:2 row_mask:0xf bank_mask:0xf
	v_mov_b32_dpp v213, v164 row_ror:2 row_mask:0xf bank_mask:0xf
	v_mov_b32_dpp v216, v163 row_ror:2 row_mask:0xf bank_mask:0xf
	v_mov_b32_dpp v217, v162 row_ror:2 row_mask:0xf bank_mask:0xf
	v_cndmask_b32_e64 v162, v218, v168, s[12:13]
	v_cndmask_b32_e64 v163, v219, v169, s[12:13]
	v_cndmask_b32_e64 v164, v220, v170, s[12:13]
	v_cndmask_b32_e64 v165, v221, v171, s[12:13]
	v_cndmask_b32_e64 v168, v51, v221, s[10:11]
	v_cndmask_b32_e64 v169, v50, v220, s[10:11]
	v_cndmask_b32_e64 v170, v49, v219, s[10:11]
	v_cndmask_b32_e64 v171, v48, v218, s[10:11]
	v_cndmask_b32_e64 v165, v51, v165, s[8:9]
	v_cndmask_b32_e64 v164, v50, v164, s[8:9]
	v_cndmask_b32_e64 v163, v49, v163, s[8:9]
	v_cndmask_b32_e64 v162, v48, v162, s[8:9]
	v_mov_b32_dpp v196, v171 row_ror:1 row_mask:0xf bank_mask:0xf
	v_mov_b32_dpp v197, v170 row_ror:1 row_mask:0xf bank_mask:0xf
	v_mov_b32_dpp v200, v169 row_ror:1 row_mask:0xf bank_mask:0xf
	v_mov_b32_dpp v201, v168 row_ror:1 row_mask:0xf bank_mask:0xf
	v_mov_b32_dpp v214, v162 row_ror:2 row_mask:0xf bank_mask:0xf
	v_mov_b32_dpp v215, v163 row_ror:2 row_mask:0xf bank_mask:0xf
	v_mov_b32_dpp v218, v164 row_ror:2 row_mask:0xf bank_mask:0xf
	v_mov_b32_dpp v219, v165 row_ror:2 row_mask:0xf bank_mask:0xf
	s_and_saveexec_b64 s[74:75], s[62:63]
	s_cbranch_execz .LBB0_1953
	s_waitcnt lgkmcnt(0)
	v_pk_fma_f32 v[164:165], v[152:153], v[212:213], v[156:157]
	s_waitcnt lgkmcnt(0)
	v_pk_fma_f32 v[162:163], v[154:155], v[216:217], v[158:159]
	v_pk_fma_f32 v[164:165], v[148:149], v[194:195], v[164:165]
	v_pk_fma_f32 v[162:163], v[150:151], v[198:199], v[162:163]
	v_pk_fma_f32 v[164:165], v[56:57], v[144:145], v[164:165]
	v_pk_fma_f32 v[162:163], v[58:59], v[146:147], v[162:163]
	v_mul_f32_e32 v185, v164, v164
	v_fmamk_f32 v185, v185, 0xbdd2d3e7, v233
	v_mul_f32_e32 v194, v165, v165
	v_mul_f32_e32 v185, v164, v185
	v_fmamk_f32 v194, v194, 0xbdd2d3e7, v233
	v_exp_f32_e32 v185, v185
	v_mul_f32_e32 v194, v165, v194
	v_exp_f32_e32 v195, v194
	s_waitcnt lgkmcnt(0)
	v_pk_fma_f32 v[170:171], v[136:137], v[214:215], v[140:141]
	v_add_f32_e32 v185, 1.0, v185
	v_rcp_f32_e32 v194, v185
	v_add_f32_e32 v185, 1.0, v195
	v_mul_f32_e32 v195, v162, v162
	v_fmamk_f32 v195, v195, 0xbdd2d3e7, v233
	v_mul_f32_e32 v195, v162, v195
	v_pk_fma_f32 v[170:171], v[132:133], v[196:197], v[170:171]
	v_exp_f32_e32 v196, v195
	v_mul_f32_e32 v195, v163, v163
	v_fmamk_f32 v195, v195, 0xbdd2d3e7, v233
	v_mul_f32_e32 v195, v163, v195
	v_exp_f32_e32 v197, v195
	v_rcp_f32_e32 v195, v185
	v_add_f32_e32 v185, 1.0, v196
	v_rcp_f32_e32 v196, v185
	v_add_f32_e32 v185, 1.0, v197
	v_rcp_f32_e32 v197, v185
	s_waitcnt lgkmcnt(0)
	v_pk_fma_f32 v[168:169], v[138:139], v[218:219], v[142:143]
	v_pk_fma_f32 v[170:171], v[48:49], v[128:129], v[170:171]
	v_pk_fma_f32 v[168:169], v[134:135], v[200:201], v[168:169]
	v_pk_mul_f32 v[164:165], v[164:165], v[194:195]
	v_pk_fma_f32 v[168:169], v[50:51], v[130:131], v[168:169]
	v_pk_mul_f32 v[162:163], v[162:163], v[196:197]
	v_pk_mul_f32 v[164:165], v[164:165], v[170:171]
	v_pk_mul_f32 v[162:163], v[162:163], v[168:169]
	v_lshlrev_b64 v[168:169], 13, v[192:193]
	v_lshl_add_u64 v[168:169], v[188:189], 0, v[168:169]
	v_cvt_pk_bf16_f32 v164, v164, v165
	v_cvt_pk_bf16_f32 v165, v162, v163
	global_store_dwordx2 v[168:169], v[164:165], off offset:8
.LBB0_1953:
	s_or_b64 exec, exec, s[74:75]
	v_cndmask_b32_e64 v165, v43, v59, s[8:9]
	v_cndmask_b32_e64 v168, v42, v58, s[8:9]
	v_cndmask_b32_e64 v185, v41, v57, s[8:9]
	v_cndmask_b32_e64 v164, v40, v56, s[8:9]
	v_cndmask_b32_e64 v171, v43, v59, s[10:11]
	v_cndmask_b32_e64 v170, v42, v58, s[10:11]
	v_cndmask_b32_e64 v163, v41, v57, s[10:11]
	v_cndmask_b32_e64 v162, v40, v56, s[10:11]
	v_mov_b32_dpp v164, v164 row_ror:2 row_mask:0xf bank_mask:0xf
	v_mov_b32_dpp v168, v168 row_ror:2 row_mask:0xf bank_mask:0xf
	v_mov_b32_dpp v169, v165 row_ror:2 row_mask:0xf bank_mask:0xf
	v_mov_b32_dpp v165, v185 row_ror:2 row_mask:0xf bank_mask:0xf
	v_mov_b32_dpp v162, v162 row_ror:1 row_mask:0xf bank_mask:0xf
	v_mov_b32_dpp v163, v163 row_ror:1 row_mask:0xf bank_mask:0xf
	v_mov_b32_dpp v170, v170 row_ror:1 row_mask:0xf bank_mask:0xf
	v_mov_b32_dpp v171, v171 row_ror:1 row_mask:0xf bank_mask:0xf
	s_waitcnt lgkmcnt(0)
	v_pk_fma_f32 v[168:169], v[154:155], v[168:169], v[158:159]
	s_waitcnt lgkmcnt(0)
	v_pk_fma_f32 v[164:165], v[152:153], v[164:165], v[156:157]
	v_cndmask_b32_e64 v188, v34, v50, s[8:9]
	s_waitcnt lgkmcnt(0)
	v_pk_fma_f32 v[162:163], v[148:149], v[162:163], v[164:165]
	s_waitcnt lgkmcnt(0)
	v_pk_fma_f32 v[164:165], v[150:151], v[170:171], v[168:169]
	v_cndmask_b32_e64 v171, v35, v51, s[8:9]
	v_cndmask_b32_e64 v193, v33, v49, s[8:9]
	v_cndmask_b32_e64 v170, v32, v48, s[8:9]
	v_cndmask_b32_e64 v185, v35, v51, s[10:11]
	v_cndmask_b32_e64 v192, v34, v50, s[10:11]
	v_cndmask_b32_e64 v169, v33, v49, s[10:11]
	v_cndmask_b32_e64 v168, v32, v48, s[10:11]
	v_mov_b32_dpp v170, v170 row_ror:2 row_mask:0xf bank_mask:0xf
	v_mov_b32_dpp v188, v188 row_ror:2 row_mask:0xf bank_mask:0xf
	v_mov_b32_dpp v189, v171 row_ror:2 row_mask:0xf bank_mask:0xf
	v_mov_b32_dpp v171, v193 row_ror:2 row_mask:0xf bank_mask:0xf
	v_mov_b32_dpp v168, v168 row_ror:1 row_mask:0xf bank_mask:0xf
	v_mov_b32_dpp v169, v169 row_ror:1 row_mask:0xf bank_mask:0xf
	v_mov_b32_dpp v192, v192 row_ror:1 row_mask:0xf bank_mask:0xf
	v_mov_b32_dpp v193, v185 row_ror:1 row_mask:0xf bank_mask:0xf
	v_pk_fma_f32 v[162:163], v[40:41], v[144:145], v[162:163]
	s_waitcnt lgkmcnt(0)
	v_pk_fma_f32 v[188:189], v[138:139], v[188:189], v[142:143]
	s_waitcnt lgkmcnt(0)
	v_pk_fma_f32 v[170:171], v[136:137], v[170:171], v[140:141]
	v_mul_f32_e32 v185, v162, v162
	s_waitcnt lgkmcnt(0)
	v_pk_fma_f32 v[168:169], v[132:133], v[168:169], v[170:171]
	s_waitcnt lgkmcnt(0)
	v_pk_fma_f32 v[170:171], v[134:135], v[192:193], v[188:189]
	v_fmamk_f32 v185, v185, 0xbdd2d3e7, v233
	v_mul_f32_e32 v188, v163, v163
	v_mul_f32_e32 v185, v162, v185
	v_fmamk_f32 v188, v188, 0xbdd2d3e7, v233
	v_exp_f32_e32 v185, v185
	v_mul_f32_e32 v188, v163, v188
	v_exp_f32_e32 v189, v188
	v_pk_fma_f32 v[164:165], v[42:43], v[146:147], v[164:165]
	v_add_f32_e32 v185, 1.0, v185
	v_rcp_f32_e32 v188, v185
	v_add_f32_e32 v185, 1.0, v189
	v_mul_f32_e32 v189, v164, v164
	v_fmamk_f32 v189, v189, 0xbdd2d3e7, v233
	v_mul_f32_e32 v189, v164, v189
	v_exp_f32_e32 v192, v189
	v_mul_f32_e32 v189, v165, v165
	v_fmamk_f32 v189, v189, 0xbdd2d3e7, v233
	v_mul_f32_e32 v189, v165, v189
	v_exp_f32_e32 v193, v189
	v_rcp_f32_e32 v189, v185
	v_add_f32_e32 v185, 1.0, v192
	v_rcp_f32_e32 v192, v185
	v_add_f32_e32 v185, 1.0, v193
	v_rcp_f32_e32 v193, v185
	v_pk_fma_f32 v[170:171], v[34:35], v[130:131], v[170:171]
	v_pk_fma_f32 v[168:169], v[32:33], v[128:129], v[168:169]
	v_pk_mul_f32 v[162:163], v[162:163], v[188:189]
	v_pk_mul_f32 v[164:165], v[164:165], v[192:193]
	v_pk_mul_f32 v[162:163], v[162:163], v[168:169]
	v_pk_mul_f32 v[164:165], v[164:165], v[170:171]
	v_cndmask_b32_e64 v169, v27, v43, s[8:9]
	v_cndmask_b32_e64 v170, v26, v42, s[8:9]
	v_cndmask_b32_e64 v185, v27, v43, s[10:11]
	v_cndmask_b32_e64 v188, v26, v42, s[10:11]
	v_cndmask_b32_e64 v189, v25, v41, s[8:9]
	v_cndmask_b32_e64 v168, v24, v40, s[8:9]
	v_mov_b32_dpp v170, v170 row_ror:2 row_mask:0xf bank_mask:0xf
	v_mov_b32_dpp v171, v169 row_ror:2 row_mask:0xf bank_mask:0xf
	v_cvt_pk_bf16_f32 v162, v162, v163
	v_cvt_pk_bf16_f32 v163, v164, v165
	v_cndmask_b32_e64 v165, v25, v41, s[10:11]
	v_cndmask_b32_e64 v164, v24, v40, s[10:11]
	v_mov_b32_dpp v168, v168 row_ror:2 row_mask:0xf bank_mask:0xf
	v_mov_b32_dpp v169, v189 row_ror:2 row_mask:0xf bank_mask:0xf
	v_mov_b32_dpp v188, v188 row_ror:1 row_mask:0xf bank_mask:0xf
	v_mov_b32_dpp v189, v185 row_ror:1 row_mask:0xf bank_mask:0xf
	v_mov_b32_dpp v164, v164 row_ror:1 row_mask:0xf bank_mask:0xf
	v_mov_b32_dpp v165, v165 row_ror:1 row_mask:0xf bank_mask:0xf
	global_store_dwordx2 v[202:203], v[162:163], off offset:8
	s_waitcnt lgkmcnt(0)
	v_pk_fma_f32 v[162:163], v[154:155], v[170:171], v[158:159]
	s_waitcnt lgkmcnt(0)
	v_pk_fma_f32 v[168:169], v[152:153], v[168:169], v[156:157]
	s_waitcnt lgkmcnt(0)
	v_pk_fma_f32 v[162:163], v[150:151], v[188:189], v[162:163]
	v_cndmask_b32_e64 v171, v19, v35, s[8:9]
	v_cndmask_b32_e64 v188, v18, v34, s[8:9]
	v_cndmask_b32_e64 v193, v17, v33, s[8:9]
	v_cndmask_b32_e64 v170, v16, v32, s[8:9]
	s_waitcnt lgkmcnt(0)
	v_pk_fma_f32 v[164:165], v[148:149], v[164:165], v[168:169]
	v_cndmask_b32_e64 v185, v19, v35, s[10:11]
	v_cndmask_b32_e64 v192, v18, v34, s[10:11]
	v_cndmask_b32_e64 v169, v17, v33, s[10:11]
	v_cndmask_b32_e64 v168, v16, v32, s[10:11]
	v_mov_b32_dpp v170, v170 row_ror:2 row_mask:0xf bank_mask:0xf
	v_mov_b32_dpp v188, v188 row_ror:2 row_mask:0xf bank_mask:0xf
	v_mov_b32_dpp v189, v171 row_ror:2 row_mask:0xf bank_mask:0xf
	v_mov_b32_dpp v171, v193 row_ror:2 row_mask:0xf bank_mask:0xf
	v_mov_b32_dpp v168, v168 row_ror:1 row_mask:0xf bank_mask:0xf
	v_mov_b32_dpp v169, v169 row_ror:1 row_mask:0xf bank_mask:0xf
	v_mov_b32_dpp v192, v192 row_ror:1 row_mask:0xf bank_mask:0xf
	v_mov_b32_dpp v193, v185 row_ror:1 row_mask:0xf bank_mask:0xf
	v_pk_fma_f32 v[164:165], v[24:25], v[144:145], v[164:165]
	s_waitcnt lgkmcnt(0)
	v_pk_fma_f32 v[188:189], v[138:139], v[188:189], v[142:143]
	s_waitcnt lgkmcnt(0)
	v_pk_fma_f32 v[170:171], v[136:137], v[170:171], v[140:141]
	v_mul_f32_e32 v185, v164, v164
	s_waitcnt lgkmcnt(0)
	v_pk_fma_f32 v[168:169], v[132:133], v[168:169], v[170:171]
	s_waitcnt lgkmcnt(0)
	v_pk_fma_f32 v[170:171], v[134:135], v[192:193], v[188:189]
	v_fmamk_f32 v185, v185, 0xbdd2d3e7, v233
	v_mul_f32_e32 v188, v165, v165
	v_mul_f32_e32 v185, v164, v185
	v_fmamk_f32 v188, v188, 0xbdd2d3e7, v233
	v_exp_f32_e32 v185, v185
	v_mul_f32_e32 v188, v165, v188
	v_exp_f32_e32 v189, v188
	v_pk_fma_f32 v[162:163], v[26:27], v[146:147], v[162:163]
	v_add_f32_e32 v185, 1.0, v185
	v_rcp_f32_e32 v188, v185
	v_add_f32_e32 v185, 1.0, v189
	v_mul_f32_e32 v189, v162, v162
	v_fmamk_f32 v189, v189, 0xbdd2d3e7, v233
	v_mul_f32_e32 v189, v162, v189
	v_exp_f32_e32 v192, v189
	v_mul_f32_e32 v189, v163, v163
	v_fmamk_f32 v189, v189, 0xbdd2d3e7, v233
	v_mul_f32_e32 v189, v163, v189
	v_exp_f32_e32 v193, v189
	v_rcp_f32_e32 v189, v185
	v_add_f32_e32 v185, 1.0, v192
	v_rcp_f32_e32 v192, v185
	v_add_f32_e32 v185, 1.0, v193
	v_rcp_f32_e32 v193, v185
	v_pk_fma_f32 v[170:171], v[18:19], v[130:131], v[170:171]
	v_pk_fma_f32 v[168:169], v[16:17], v[128:129], v[168:169]
	v_pk_mul_f32 v[164:165], v[164:165], v[188:189]
	v_pk_mul_f32 v[162:163], v[162:163], v[192:193]
	v_pk_mul_f32 v[164:165], v[164:165], v[168:169]
	v_pk_mul_f32 v[162:163], v[162:163], v[170:171]
	v_cndmask_b32_e64 v169, v11, v27, s[8:9]
	v_cndmask_b32_e64 v170, v10, v26, s[8:9]
	v_cndmask_b32_e64 v189, v9, v25, s[8:9]
	v_cndmask_b32_e64 v168, v8, v24, s[8:9]
	v_cvt_pk_bf16_f32 v164, v164, v165
	v_cvt_pk_bf16_f32 v165, v162, v163
	v_cndmask_b32_e64 v185, v11, v27, s[10:11]
	v_cndmask_b32_e64 v188, v10, v26, s[10:11]
	v_cndmask_b32_e64 v163, v9, v25, s[10:11]
	v_cndmask_b32_e64 v162, v8, v24, s[10:11]
	v_mov_b32_dpp v168, v168 row_ror:2 row_mask:0xf bank_mask:0xf
	v_mov_b32_dpp v170, v170 row_ror:2 row_mask:0xf bank_mask:0xf
	v_mov_b32_dpp v171, v169 row_ror:2 row_mask:0xf bank_mask:0xf
	v_mov_b32_dpp v169, v189 row_ror:2 row_mask:0xf bank_mask:0xf
	v_mov_b32_dpp v162, v162 row_ror:1 row_mask:0xf bank_mask:0xf
	v_mov_b32_dpp v163, v163 row_ror:1 row_mask:0xf bank_mask:0xf
	v_mov_b32_dpp v188, v188 row_ror:1 row_mask:0xf bank_mask:0xf
	v_mov_b32_dpp v189, v185 row_ror:1 row_mask:0xf bank_mask:0xf
	s_waitcnt lgkmcnt(0)
	v_pk_fma_f32 v[154:155], v[154:155], v[170:171], v[158:159]
	s_waitcnt lgkmcnt(0)
	v_pk_fma_f32 v[152:153], v[152:153], v[168:169], v[156:157]
	v_cndmask_b32_e64 v158, v1, v17, s[8:9]
	s_waitcnt lgkmcnt(0)
	v_pk_fma_f32 v[148:149], v[148:149], v[162:163], v[152:153]
	s_waitcnt lgkmcnt(0)
	v_pk_fma_f32 v[150:151], v[150:151], v[188:189], v[154:155]
	v_cndmask_b32_e64 v153, v3, v19, s[8:9]
	v_cndmask_b32_e64 v152, v0, v16, s[8:9]
	v_pk_fma_f32 v[146:147], v[10:11], v[146:147], v[150:151]
	v_cndmask_b32_e64 v151, v1, v17, s[10:11]
	v_cndmask_b32_e64 v150, v0, v16, s[10:11]
	v_mov_b32_dpp v152, v152 row_ror:2 row_mask:0xf bank_mask:0xf
	v_mov_b32_dpp v155, v153 row_ror:2 row_mask:0xf bank_mask:0xf
	v_mov_b32_dpp v153, v158 row_ror:2 row_mask:0xf bank_mask:0xf
	v_mov_b32_dpp v150, v150 row_ror:1 row_mask:0xf bank_mask:0xf
	v_mov_b32_dpp v151, v151 row_ror:1 row_mask:0xf bank_mask:0xf
	v_cndmask_b32_e64 v154, v2, v18, s[8:9]
	v_pk_fma_f32 v[144:145], v[8:9], v[144:145], v[148:149]
	s_waitcnt lgkmcnt(0)
	v_pk_fma_f32 v[136:137], v[136:137], v[152:153], v[140:141]
	v_cndmask_b32_e64 v157, v3, v19, s[10:11]
	v_cndmask_b32_e64 v156, v2, v18, s[10:11]
	v_mov_b32_dpp v154, v154 row_ror:2 row_mask:0xf bank_mask:0xf
	s_waitcnt lgkmcnt(0)
	v_pk_fma_f32 v[132:133], v[132:133], v[150:151], v[136:137]
	v_mul_f32_e32 v136, v144, v144
	v_mul_f32_e32 v137, v145, v145
	v_mov_b32_dpp v156, v156 row_ror:1 row_mask:0xf bank_mask:0xf
	v_mov_b32_dpp v157, v157 row_ror:1 row_mask:0xf bank_mask:0xf
	v_fmamk_f32 v136, v136, 0xbdd2d3e7, v233
	v_fmamk_f32 v137, v137, 0xbdd2d3e7, v233
	v_mul_f32_e32 v136, v144, v136
	v_mul_f32_e32 v137, v145, v137
	v_exp_f32_e32 v136, v136
	v_exp_f32_e32 v137, v137
	s_waitcnt lgkmcnt(0)
	v_pk_fma_f32 v[138:139], v[138:139], v[154:155], v[142:143]
	v_pk_fma_f32 v[128:129], v[0:1], v[128:129], v[132:133]
	s_waitcnt lgkmcnt(0)
	v_pk_fma_f32 v[134:135], v[134:135], v[156:157], v[138:139]
	global_store_dwordx2 v[204:205], v[164:165], off offset:8
	v_pk_fma_f32 v[130:131], v[2:3], v[130:131], v[134:135]
	v_add_f32_e32 v134, 1.0, v136
	v_add_f32_e32 v135, 1.0, v137
	v_mul_f32_e32 v136, v146, v146
	v_mul_f32_e32 v137, v147, v147
	v_fmamk_f32 v136, v136, 0xbdd2d3e7, v233
	v_fmamk_f32 v137, v137, 0xbdd2d3e7, v233
	v_mul_f32_e32 v136, v146, v136
	v_mul_f32_e32 v137, v147, v137
	v_exp_f32_e32 v136, v136
	v_exp_f32_e32 v137, v137
	v_rcp_f32_e32 v134, v134
	v_rcp_f32_e32 v135, v135
	v_add_f32_e32 v136, 1.0, v136
	v_add_f32_e32 v137, 1.0, v137
	v_rcp_f32_e32 v136, v136
	v_rcp_f32_e32 v137, v137
	v_pk_mul_f32 v[132:133], v[144:145], v[134:135]
	s_nop 0
	v_pk_mul_f32 v[128:129], v[132:133], v[128:129]
	v_pk_mul_f32 v[132:133], v[146:147], v[136:137]
	v_cvt_pk_bf16_f32 v128, v128, v129
	v_pk_mul_f32 v[130:131], v[132:133], v[130:131]
	s_nop 0
	v_cvt_pk_bf16_f32 v129, v130, v131
	global_store_dwordx2 v[210:211], v[128:129], off offset:8
	s_and_saveexec_b64 s[74:75], s[34:35]
	s_cbranch_execz .LBB0_1955
	v_cvt_pk_bf16_f32 v128, v120, v121
	v_cvt_pk_bf16_f32 v129, v122, v123
	global_store_dwordx2 v[208:209], v[128:129], off offset:8

	.amdhsa_kernel _Z8mega_fwd4Args
		.amdhsa_group_segment_fixed_size 0
		.amdhsa_private_segment_fixed_size 0
		.amdhsa_kernarg_size 464
		.amdhsa_user_sgpr_count 2
		.amdhsa_user_sgpr_dispatch_ptr 0
		.amdhsa_user_sgpr_queue_ptr 0
		.amdhsa_user_sgpr_kernarg_segment_ptr 1
		.amdhsa_user_sgpr_dispatch_id 0
		.amdhsa_user_sgpr_kernarg_preload_length 0
		.amdhsa_user_sgpr_kernarg_preload_offset 0
		.amdhsa_user_sgpr_private_segment_size 0
		.amdhsa_uses_dynamic_stack 0
		.amdhsa_enable_private_segment 0
		.amdhsa_system_sgpr_workgroup_id_x 1
		.amdhsa_system_sgpr_workgroup_id_y 0
		.amdhsa_system_sgpr_workgroup_id_z 0
		.amdhsa_system_sgpr_workgroup_info 0
		.amdhsa_system_vgpr_workitem_id 0
		.amdhsa_next_free_vgpr 256
		.amdhsa_next_free_sgpr 102
		.amdhsa_accum_offset 256
		.amdhsa_reserve_vcc 1
		.amdhsa_float_round_mode_32 0
		.amdhsa_float_round_mode_16_64 0
		.amdhsa_float_denorm_mode_32 3
		.amdhsa_float_denorm_mode_16_64 3
		.amdhsa_dx10_clamp 1
		.amdhsa_ieee_mode 1
		.amdhsa_fp16_overflow 0
		.amdhsa_tg_split 0
		.amdhsa_exception_fp_ieee_invalid_op 0
		.amdhsa_exception_fp_denorm_src 0
		.amdhsa_exception_fp_ieee_div_zero 0
		.amdhsa_exception_fp_ieee_overflow 0
		.amdhsa_exception_fp_ieee_underflow 0
		.amdhsa_exception_fp_ieee_inexact 0
		.amdhsa_exception_int_div_zero 0
	.end_amdhsa_kernel

amdhsa.kernels:
  - .agpr_count:     0
    .args:
      - .offset:         0
        .size:           208
        .value_kind:     by_value
      - .offset:         208
        .size:           4
        .value_kind:     hidden_block_count_x
      - .offset:         212
        .size:           4
        .value_kind:     hidden_block_count_y
      - .offset:         216
        .size:           4
        .value_kind:     hidden_block_count_z
      - .offset:         220
        .size:           2
        .value_kind:     hidden_group_size_x
      - .offset:         222
        .size:           2
        .value_kind:     hidden_group_size_y
      - .offset:         224
        .size:           2
        .value_kind:     hidden_group_size_z
      - .offset:         226
        .size:           2
        .value_kind:     hidden_remainder_x
      - .offset:         228
        .size:           2
        .value_kind:     hidden_remainder_y
      - .offset:         230
        .size:           2
        .value_kind:     hidden_remainder_z
      - .offset:         248
        .size:           8
        .value_kind:     hidden_global_offset_x
      - .offset:         256
        .size:           8
        .value_kind:     hidden_global_offset_y
      - .offset:         264
        .size:           8
        .value_kind:     hidden_global_offset_z
      - .offset:         272
        .size:           2
        .value_kind:     hidden_grid_dims
      - .offset:         328
        .size:           4
        .value_kind:     hidden_dynamic_lds_size
    .group_segment_fixed_size: 0
    .kernarg_segment_align: 8
    .kernarg_segment_size: 464
    .language:       OpenCL C
    .language_version:
      - 2
      - 0
    .max_flat_workgroup_size: 512
    .name:           _Z8mega_fwd4Args
    .private_segment_fixed_size: 0
    .sgpr_count:     108
    .sgpr_spill_count: 172
    .symbol:         _Z8mega_fwd4Args.kd
    .uniform_work_group_size: 1
    .uses_dynamic_stack: false
    .vgpr_count:     256
    .vgpr_spill_count: 0
    .wavefront_size: 64
